# GEMM main loops: loop-control scalar ops moved ahead of the phase-closing barrier (back-edge rotation)
# baseline (speedup 1.0000x reference)
.LBB0_234:
	s_add_u32 s22, s20, 0xfffc0080
	s_addc_u32 s23, s21, -1
	s_add_i32 s47, 0, 0x10000
	s_cmp_eq_u32 s46, 12
	s_cselect_b32 s25, s15, s23
	s_cselect_b32 s24, s42, s22
	v_add_u32_e32 v144, s47, v160
	s_cselect_b32 s23, s13, s45
	s_cselect_b32 s22, s43, s44
	s_add_i32 s50, 0, 0x14000
	ds_read_b128 v[140:143], v144
	ds_read_b128 v[164:167], v144 offset:1024
	ds_read_b128 v[168:171], v144 offset:2048
	ds_read_b128 v[172:175], v144 offset:3072
	v_add_u32_e32 v144, s50, v160
	ds_read_b128 v[176:179], v144
	ds_read_b128 v[182:185], v144 offset:1024
	ds_read_b128 v[186:189], v144 offset:2048
	ds_read_b128 v[204:207], v144 offset:3072
	v_lshl_add_u64 v[190:191], s[20:21], 0, v[136:137]
	s_add_i32 m0, s31, 0xc000
	ds_read_b128 v[208:211], v163
	ds_read_b128 v[212:215], v163 offset:1024
	ds_read_b128 v[216:219], v163 offset:2048
	ds_read_b128 v[220:223], v163 offset:3072
	ds_read_b128 v[224:227], v163 offset:4096
	ds_read_b128 v[228:231], v163 offset:5120
	ds_read_b128 v[232:235], v163 offset:6144
	ds_read_b128 v[236:239], v163 offset:7168
	global_load_lds_dwordx4 v[190:191], off
	v_lshl_add_u64 v[190:191], s[20:21], 0, v[138:139]
	s_add_i32 m0, s31, 0xe000
	s_nop 0
	global_load_lds_dwordx4 v[190:191], off
	s_waitcnt vmcnt(8)
	s_waitcnt lgkmcnt(0)
	s_barrier
	s_setprio 1
	s_waitcnt lgkmcnt(0)
	v_mfma_f32_16x16x32_bf16 v[126:129], v[140:143], v[208:211], v[126:129]
	v_mfma_f32_16x16x32_bf16 v[122:125], v[168:171], v[208:211], v[122:125]
	v_mfma_f32_16x16x32_bf16 v[110:113], v[140:143], v[216:219], v[110:113]
	v_mfma_f32_16x16x32_bf16 v[106:109], v[168:171], v[216:219], v[106:109]
	v_mfma_f32_16x16x32_bf16 v[94:97], v[140:143], v[224:227], v[94:97]
	v_mfma_f32_16x16x32_bf16 v[90:93], v[168:171], v[224:227], v[90:93]
	v_mfma_f32_16x16x32_bf16 v[78:81], v[140:143], v[232:235], v[78:81]
	v_mfma_f32_16x16x32_bf16 v[74:77], v[168:171], v[232:235], v[74:77]
	v_mfma_f32_16x16x32_bf16 v[126:129], v[164:167], v[212:215], v[126:129]
	v_mfma_f32_16x16x32_bf16 v[122:125], v[172:175], v[212:215], v[122:125]
	v_mfma_f32_16x16x32_bf16 v[110:113], v[164:167], v[220:223], v[110:113]
	v_mfma_f32_16x16x32_bf16 v[106:109], v[172:175], v[220:223], v[106:109]
	v_mfma_f32_16x16x32_bf16 v[94:97], v[164:167], v[228:231], v[94:97]
	v_mfma_f32_16x16x32_bf16 v[90:93], v[172:175], v[228:231], v[90:93]
	v_mfma_f32_16x16x32_bf16 v[78:81], v[164:167], v[236:239], v[78:81]
	v_mfma_f32_16x16x32_bf16 v[74:77], v[172:175], v[236:239], v[74:77]
	s_setprio 0
	s_setprio 1
	v_mfma_f32_16x16x32_bf16 v[118:121], v[176:179], v[208:211], v[118:121]
	v_mfma_f32_16x16x32_bf16 v[114:117], v[186:189], v[208:211], v[114:117]
	v_mfma_f32_16x16x32_bf16 v[102:105], v[176:179], v[216:219], v[102:105]
	v_mfma_f32_16x16x32_bf16 v[98:101], v[186:189], v[216:219], v[98:101]
	v_mfma_f32_16x16x32_bf16 v[86:89], v[176:179], v[224:227], v[86:89]
	v_mfma_f32_16x16x32_bf16 v[82:85], v[186:189], v[224:227], v[82:85]
	v_mfma_f32_16x16x32_bf16 v[70:73], v[176:179], v[232:235], v[70:73]
	v_mfma_f32_16x16x32_bf16 v[66:69], v[186:189], v[232:235], v[66:69]
	v_mfma_f32_16x16x32_bf16 v[118:121], v[182:185], v[212:215], v[118:121]
	v_mfma_f32_16x16x32_bf16 v[114:117], v[204:207], v[212:215], v[114:117]
	v_mfma_f32_16x16x32_bf16 v[102:105], v[182:185], v[220:223], v[102:105]
	v_mfma_f32_16x16x32_bf16 v[98:101], v[204:207], v[220:223], v[98:101]
	v_mfma_f32_16x16x32_bf16 v[86:89], v[182:185], v[228:231], v[86:89]
	v_mfma_f32_16x16x32_bf16 v[82:85], v[204:207], v[228:231], v[82:85]
	v_mfma_f32_16x16x32_bf16 v[70:73], v[182:185], v[236:239], v[70:73]
	v_mfma_f32_16x16x32_bf16 v[66:69], v[204:207], v[236:239], v[66:69]
	s_setprio 0
	s_barrier
	s_add_i32 s47, s47, s30
	v_lshl_add_u64 v[190:191], s[22:23], 0, v[0:1]
	s_mov_b32 m0, s47
	ds_read_b128 v[208:211], v163 offset:16384
	ds_read_b128 v[212:215], v163 offset:17408
	ds_read_b128 v[216:219], v163 offset:18432
	ds_read_b128 v[220:223], v163 offset:19456
	ds_read_b128 v[224:227], v163 offset:20480
	ds_read_b128 v[228:231], v163 offset:21504
	ds_read_b128 v[232:235], v163 offset:22528
	ds_read_b128 v[236:239], v163 offset:23552
	global_load_lds_dwordx4 v[190:191], off
	s_add_i32 m0, s47, 0x2000
	s_add_u32 s48, s22, 0x40000
	v_lshl_add_u64 v[240:241], s[22:23], 0, v[130:131]
	s_addc_u32 s49, s23, 0
	s_add_i32 s47, s50, s30
	global_load_lds_dwordx4 v[240:241], off
	v_lshl_add_u64 v[242:243], s[48:49], 0, v[0:1]
	s_mov_b32 m0, s47
	v_lshl_add_u64 v[244:245], s[24:25], 0, v[132:133]
	global_load_lds_dwordx4 v[242:243], off
	v_lshl_add_u64 v[242:243], s[48:49], 0, v[130:131]
	s_add_i32 m0, s47, 0x2000
	s_nop 0
	global_load_lds_dwordx4 v[242:243], off
	v_lshl_add_u64 v[242:243], s[24:25], 0, v[134:135]
	s_mov_b32 m0, s31
	s_nop 0
	global_load_lds_dwordx4 v[242:243], off
	s_mov_b32 m0, s34
	s_nop 0
	global_load_lds_dwordx4 v[244:245], off
	s_waitcnt vmcnt(8)
	s_waitcnt lgkmcnt(0)
	s_barrier
	s_setprio 1
	s_waitcnt lgkmcnt(0)
	v_mfma_f32_16x16x32_bf16 v[62:65], v[140:143], v[208:211], v[62:65]
	v_mfma_f32_16x16x32_bf16 v[58:61], v[168:171], v[208:211], v[58:61]
	v_mfma_f32_16x16x32_bf16 v[46:49], v[140:143], v[216:219], v[46:49]
	v_mfma_f32_16x16x32_bf16 v[42:45], v[168:171], v[216:219], v[42:45]
	v_mfma_f32_16x16x32_bf16 v[30:33], v[140:143], v[224:227], v[30:33]
	v_mfma_f32_16x16x32_bf16 v[26:29], v[168:171], v[224:227], v[26:29]
	v_mfma_f32_16x16x32_bf16 v[14:17], v[140:143], v[232:235], v[14:17]
	v_mfma_f32_16x16x32_bf16 v[10:13], v[168:171], v[232:235], v[10:13]
	v_mfma_f32_16x16x32_bf16 v[62:65], v[164:167], v[212:215], v[62:65]
	v_mfma_f32_16x16x32_bf16 v[58:61], v[172:175], v[212:215], v[58:61]
	v_mfma_f32_16x16x32_bf16 v[46:49], v[164:167], v[220:223], v[46:49]
	v_mfma_f32_16x16x32_bf16 v[42:45], v[172:175], v[220:223], v[42:45]
	v_mfma_f32_16x16x32_bf16 v[30:33], v[164:167], v[228:231], v[30:33]
	v_mfma_f32_16x16x32_bf16 v[26:29], v[172:175], v[228:231], v[26:29]
	v_mfma_f32_16x16x32_bf16 v[14:17], v[164:167], v[236:239], v[14:17]
	v_mfma_f32_16x16x32_bf16 v[10:13], v[172:175], v[236:239], v[10:13]
	s_setprio 0
	s_setprio 1
	v_mfma_f32_16x16x32_bf16 v[54:57], v[176:179], v[208:211], v[54:57]
	v_mfma_f32_16x16x32_bf16 v[50:53], v[186:189], v[208:211], v[50:53]
	v_mfma_f32_16x16x32_bf16 v[38:41], v[176:179], v[216:219], v[38:41]
	v_mfma_f32_16x16x32_bf16 v[34:37], v[186:189], v[216:219], v[34:37]
	v_mfma_f32_16x16x32_bf16 v[22:25], v[176:179], v[224:227], v[22:25]
	v_mfma_f32_16x16x32_bf16 v[18:21], v[186:189], v[224:227], v[18:21]
	v_mfma_f32_16x16x32_bf16 v[6:9], v[176:179], v[232:235], v[6:9]
	v_mfma_f32_16x16x32_bf16 v[2:5], v[186:189], v[232:235], v[2:5]
	v_mfma_f32_16x16x32_bf16 v[54:57], v[182:185], v[212:215], v[54:57]
	v_mfma_f32_16x16x32_bf16 v[50:53], v[204:207], v[212:215], v[50:53]
	v_mfma_f32_16x16x32_bf16 v[38:41], v[182:185], v[220:223], v[38:41]
	v_mfma_f32_16x16x32_bf16 v[34:37], v[204:207], v[220:223], v[34:37]
	v_mfma_f32_16x16x32_bf16 v[22:25], v[182:185], v[228:231], v[22:25]
	v_mfma_f32_16x16x32_bf16 v[18:21], v[204:207], v[228:231], v[18:21]
	v_mfma_f32_16x16x32_bf16 v[6:9], v[182:185], v[236:239], v[6:9]
	v_mfma_f32_16x16x32_bf16 v[2:5], v[204:207], v[236:239], v[2:5]
	s_setprio 0
	s_barrier
	s_add_i32 s47, 0, 0x18000
	v_add_u32_e32 v144, s47, v160
	s_add_i32 s48, 0, 0x1c000
	ds_read_b128 v[140:143], v144
	ds_read_b128 v[164:167], v144 offset:1024
	ds_read_b128 v[168:171], v144 offset:2048
	ds_read_b128 v[172:175], v144 offset:3072
	v_add_u32_e32 v144, s48, v160
	ds_read_b128 v[176:179], v144
	ds_read_b128 v[182:185], v144 offset:1024
	ds_read_b128 v[186:189], v144 offset:2048
	ds_read_b128 v[204:207], v144 offset:3072
	s_add_u32 s24, s24, 0x40000
	s_addc_u32 s25, s25, 0
	s_mov_b32 m0, s35
	v_lshl_add_u64 v[246:247], s[24:25], 0, v[134:135]
	ds_read_b128 v[208:211], v163 offset:32768
	ds_read_b128 v[212:215], v163 offset:33792
	ds_read_b128 v[216:219], v163 offset:34816
	ds_read_b128 v[220:223], v163 offset:35840
	ds_read_b128 v[224:227], v163 offset:36864
	ds_read_b128 v[228:231], v163 offset:37888
	ds_read_b128 v[232:235], v163 offset:38912
	ds_read_b128 v[236:239], v163 offset:39936
	global_load_lds_dwordx4 v[246:247], off
	v_lshl_add_u64 v[246:247], s[24:25], 0, v[132:133]
	s_mov_b32 m0, s36
	s_nop 0
	global_load_lds_dwordx4 v[246:247], off
	s_waitcnt vmcnt(8)
	s_waitcnt lgkmcnt(0)
	s_barrier
	s_setprio 1
	s_waitcnt lgkmcnt(0)
	v_mfma_f32_16x16x32_bf16 v[126:129], v[140:143], v[208:211], v[126:129]
	v_mfma_f32_16x16x32_bf16 v[122:125], v[168:171], v[208:211], v[122:125]
	v_mfma_f32_16x16x32_bf16 v[110:113], v[140:143], v[216:219], v[110:113]
	v_mfma_f32_16x16x32_bf16 v[106:109], v[168:171], v[216:219], v[106:109]
	v_mfma_f32_16x16x32_bf16 v[94:97], v[140:143], v[224:227], v[94:97]
	v_mfma_f32_16x16x32_bf16 v[90:93], v[168:171], v[224:227], v[90:93]
	v_mfma_f32_16x16x32_bf16 v[78:81], v[140:143], v[232:235], v[78:81]
	v_mfma_f32_16x16x32_bf16 v[74:77], v[168:171], v[232:235], v[74:77]
	v_mfma_f32_16x16x32_bf16 v[126:129], v[164:167], v[212:215], v[126:129]
	v_mfma_f32_16x16x32_bf16 v[122:125], v[172:175], v[212:215], v[122:125]
	v_mfma_f32_16x16x32_bf16 v[110:113], v[164:167], v[220:223], v[110:113]
	v_mfma_f32_16x16x32_bf16 v[106:109], v[172:175], v[220:223], v[106:109]
	v_mfma_f32_16x16x32_bf16 v[94:97], v[164:167], v[228:231], v[94:97]
	v_mfma_f32_16x16x32_bf16 v[90:93], v[172:175], v[228:231], v[90:93]
	v_mfma_f32_16x16x32_bf16 v[78:81], v[164:167], v[236:239], v[78:81]
	v_mfma_f32_16x16x32_bf16 v[74:77], v[172:175], v[236:239], v[74:77]
	s_setprio 0
	s_setprio 1
	v_mfma_f32_16x16x32_bf16 v[118:121], v[176:179], v[208:211], v[118:121]
	v_mfma_f32_16x16x32_bf16 v[114:117], v[186:189], v[208:211], v[114:117]
	v_mfma_f32_16x16x32_bf16 v[102:105], v[176:179], v[216:219], v[102:105]
	v_mfma_f32_16x16x32_bf16 v[98:101], v[186:189], v[216:219], v[98:101]
	v_mfma_f32_16x16x32_bf16 v[86:89], v[176:179], v[224:227], v[86:89]
	v_mfma_f32_16x16x32_bf16 v[82:85], v[186:189], v[224:227], v[82:85]
	v_mfma_f32_16x16x32_bf16 v[70:73], v[176:179], v[232:235], v[70:73]
	v_mfma_f32_16x16x32_bf16 v[66:69], v[186:189], v[232:235], v[66:69]
	v_mfma_f32_16x16x32_bf16 v[118:121], v[182:185], v[212:215], v[118:121]
	v_mfma_f32_16x16x32_bf16 v[114:117], v[204:207], v[212:215], v[114:117]
	v_mfma_f32_16x16x32_bf16 v[102:105], v[182:185], v[220:223], v[102:105]
	v_mfma_f32_16x16x32_bf16 v[98:101], v[204:207], v[220:223], v[98:101]
	v_mfma_f32_16x16x32_bf16 v[86:89], v[182:185], v[228:231], v[86:89]
	v_mfma_f32_16x16x32_bf16 v[82:85], v[204:207], v[228:231], v[82:85]
	v_mfma_f32_16x16x32_bf16 v[70:73], v[182:185], v[236:239], v[70:73]
	v_mfma_f32_16x16x32_bf16 v[66:69], v[204:207], v[236:239], v[66:69]
	s_setprio 0
	s_barrier
	s_add_i32 s24, s47, s30
	v_lshl_add_u64 v[190:191], v[190:191], 0, s[80:81]
	s_mov_b32 m0, s24
	ds_read_b128 v[208:211], v163 offset:49152
	ds_read_b128 v[212:215], v163 offset:50176
	ds_read_b128 v[216:219], v163 offset:51200
	ds_read_b128 v[220:223], v163 offset:52224
	ds_read_b128 v[224:227], v163 offset:53248
	ds_read_b128 v[228:231], v163 offset:54272
	ds_read_b128 v[232:235], v163 offset:55296
	ds_read_b128 v[236:239], v163 offset:56320
	global_load_lds_dwordx4 v[190:191], off
	s_add_i32 m0, s24, 0x2000
	s_add_u32 s22, s22, 0x40080
	v_lshl_add_u64 v[190:191], v[240:241], 0, s[80:81]
	s_addc_u32 s23, s23, 0
	s_add_i32 s24, s48, s30
	global_load_lds_dwordx4 v[190:191], off
	v_lshl_add_u64 v[190:191], s[22:23], 0, v[0:1]
	s_mov_b32 m0, s24
	s_nop 0
	global_load_lds_dwordx4 v[190:191], off
	v_lshl_add_u64 v[190:191], s[22:23], 0, v[130:131]
	s_add_i32 m0, s24, 0x2000
	s_nop 0
	global_load_lds_dwordx4 v[190:191], off
	v_lshl_add_u64 v[190:191], v[242:243], 0, s[80:81]
	s_mov_b32 m0, s37
	s_nop 0
	global_load_lds_dwordx4 v[190:191], off
	v_lshl_add_u64 v[190:191], v[244:245], 0, s[80:81]
	s_mov_b32 m0, s38
	s_nop 0
	global_load_lds_dwordx4 v[190:191], off
	s_waitcnt vmcnt(8)
	s_waitcnt lgkmcnt(0)
	s_barrier
	s_setprio 1
	s_waitcnt lgkmcnt(0)
	v_mfma_f32_16x16x32_bf16 v[62:65], v[140:143], v[208:211], v[62:65]
	v_mfma_f32_16x16x32_bf16 v[58:61], v[168:171], v[208:211], v[58:61]
	v_mfma_f32_16x16x32_bf16 v[46:49], v[140:143], v[216:219], v[46:49]
	v_mfma_f32_16x16x32_bf16 v[42:45], v[168:171], v[216:219], v[42:45]
	v_mfma_f32_16x16x32_bf16 v[30:33], v[140:143], v[224:227], v[30:33]
	v_mfma_f32_16x16x32_bf16 v[26:29], v[168:171], v[224:227], v[26:29]
	v_mfma_f32_16x16x32_bf16 v[14:17], v[140:143], v[232:235], v[14:17]
	v_mfma_f32_16x16x32_bf16 v[10:13], v[168:171], v[232:235], v[10:13]
	v_mfma_f32_16x16x32_bf16 v[62:65], v[164:167], v[212:215], v[62:65]
	v_mfma_f32_16x16x32_bf16 v[58:61], v[172:175], v[212:215], v[58:61]
	v_mfma_f32_16x16x32_bf16 v[46:49], v[164:167], v[220:223], v[46:49]
	v_mfma_f32_16x16x32_bf16 v[42:45], v[172:175], v[220:223], v[42:45]
	v_mfma_f32_16x16x32_bf16 v[30:33], v[164:167], v[228:231], v[30:33]
	v_mfma_f32_16x16x32_bf16 v[26:29], v[172:175], v[228:231], v[26:29]
	v_mfma_f32_16x16x32_bf16 v[14:17], v[164:167], v[236:239], v[14:17]
	v_mfma_f32_16x16x32_bf16 v[10:13], v[172:175], v[236:239], v[10:13]
	s_setprio 0
	s_setprio 1
	v_mfma_f32_16x16x32_bf16 v[54:57], v[176:179], v[208:211], v[54:57]
	v_mfma_f32_16x16x32_bf16 v[50:53], v[186:189], v[208:211], v[50:53]
	v_mfma_f32_16x16x32_bf16 v[38:41], v[176:179], v[216:219], v[38:41]
	v_mfma_f32_16x16x32_bf16 v[34:37], v[186:189], v[216:219], v[34:37]
	v_mfma_f32_16x16x32_bf16 v[22:25], v[176:179], v[224:227], v[22:25]
	v_mfma_f32_16x16x32_bf16 v[18:21], v[186:189], v[224:227], v[18:21]
	v_mfma_f32_16x16x32_bf16 v[6:9], v[176:179], v[232:235], v[6:9]
	v_mfma_f32_16x16x32_bf16 v[2:5], v[186:189], v[232:235], v[2:5]
	v_mfma_f32_16x16x32_bf16 v[54:57], v[182:185], v[212:215], v[54:57]
	v_mfma_f32_16x16x32_bf16 v[50:53], v[204:207], v[212:215], v[50:53]
	v_mfma_f32_16x16x32_bf16 v[38:41], v[182:185], v[220:223], v[38:41]
	v_mfma_f32_16x16x32_bf16 v[34:37], v[204:207], v[220:223], v[34:37]
	v_mfma_f32_16x16x32_bf16 v[22:25], v[182:185], v[228:231], v[22:25]
	v_mfma_f32_16x16x32_bf16 v[18:21], v[204:207], v[228:231], v[18:21]
	v_mfma_f32_16x16x32_bf16 v[6:9], v[182:185], v[236:239], v[6:9]
	v_mfma_f32_16x16x32_bf16 v[2:5], v[204:207], v[236:239], v[2:5]
	s_add_i32 s46, s46, 2
	s_add_u32 s20, s20, 0x100
	s_addc_u32 s21, s21, 0
	s_add_u32 s44, s44, 0x100
	s_addc_u32 s45, s45, 0
	s_cmp_gt_u32 s46, 13
	s_setprio 0
	s_barrier
	s_cbranch_scc0 .LBB0_234
	s_and_b64 vcc, exec, s[10:11]
	s_cbranch_vccz .LBB0_237
	s_barrier

.LBB0_310:
	s_add_u32 s22, s20, 0x100
	s_addc_u32 s23, s21, 0
	s_add_i32 s50, 0, 0x10000
	s_cmp_eq_u32 s49, 40
	s_cselect_b32 s27, s13, s23
	s_cselect_b32 s26, s12, s22
	v_add_u32_e32 v140, s50, v143
	s_cselect_b32 s25, s19, s48
	s_cselect_b32 s24, s18, s47
	s_add_i32 s51, 0, 0x14000
	ds_read_b128 v[136:139], v140
	ds_read_b128 v[162:165], v140 offset:1024
	ds_read_b128 v[166:169], v140 offset:2048
	ds_read_b128 v[170:173], v140 offset:3072
	v_add_u32_e32 v140, s51, v143
	ds_read_b128 v[174:177], v140
	ds_read_b128 v[182:185], v140 offset:1024
	ds_read_b128 v[186:189], v140 offset:2048
	ds_read_b128 v[204:207], v140 offset:3072
	v_lshl_add_u64 v[140:141], s[20:21], 0, v[132:133]
	s_add_i32 m0, s35, 0xc000
	ds_read_b128 v[208:211], v145
	ds_read_b128 v[212:215], v145 offset:1024
	ds_read_b128 v[216:219], v145 offset:2048
	ds_read_b128 v[220:223], v145 offset:3072
	ds_read_b128 v[224:227], v145 offset:4096
	ds_read_b128 v[228:231], v145 offset:5120
	ds_read_b128 v[232:235], v145 offset:6144
	ds_read_b128 v[236:239], v145 offset:7168
	global_load_lds_dwordx4 v[140:141], off
	v_lshl_add_u64 v[140:141], s[20:21], 0, v[134:135]
	s_add_i32 m0, s35, 0xe000
	s_nop 0
	global_load_lds_dwordx4 v[140:141], off
	s_waitcnt vmcnt(8)
	s_waitcnt lgkmcnt(0)
	s_barrier
	s_setprio 1
	s_waitcnt lgkmcnt(0)
	v_mfma_f32_16x16x32_bf16 v[126:129], v[136:139], v[208:211], v[126:129]
	v_mfma_f32_16x16x32_bf16 v[122:125], v[166:169], v[208:211], v[122:125]
	v_mfma_f32_16x16x32_bf16 v[110:113], v[136:139], v[216:219], v[110:113]
	v_mfma_f32_16x16x32_bf16 v[106:109], v[166:169], v[216:219], v[106:109]
	v_mfma_f32_16x16x32_bf16 v[94:97], v[136:139], v[224:227], v[94:97]
	v_mfma_f32_16x16x32_bf16 v[90:93], v[166:169], v[224:227], v[90:93]
	v_mfma_f32_16x16x32_bf16 v[78:81], v[136:139], v[232:235], v[78:81]
	v_mfma_f32_16x16x32_bf16 v[74:77], v[166:169], v[232:235], v[74:77]
	v_mfma_f32_16x16x32_bf16 v[126:129], v[162:165], v[212:215], v[126:129]
	v_mfma_f32_16x16x32_bf16 v[122:125], v[170:173], v[212:215], v[122:125]
	v_mfma_f32_16x16x32_bf16 v[110:113], v[162:165], v[220:223], v[110:113]
	v_mfma_f32_16x16x32_bf16 v[106:109], v[170:173], v[220:223], v[106:109]
	v_mfma_f32_16x16x32_bf16 v[94:97], v[162:165], v[228:231], v[94:97]
	v_mfma_f32_16x16x32_bf16 v[90:93], v[170:173], v[228:231], v[90:93]
	v_mfma_f32_16x16x32_bf16 v[78:81], v[162:165], v[236:239], v[78:81]
	v_mfma_f32_16x16x32_bf16 v[74:77], v[170:173], v[236:239], v[74:77]
	s_setprio 0
	s_setprio 1
	v_mfma_f32_16x16x32_bf16 v[118:121], v[174:177], v[208:211], v[118:121]
	v_mfma_f32_16x16x32_bf16 v[114:117], v[186:189], v[208:211], v[114:117]
	v_mfma_f32_16x16x32_bf16 v[102:105], v[174:177], v[216:219], v[102:105]
	v_mfma_f32_16x16x32_bf16 v[98:101], v[186:189], v[216:219], v[98:101]
	v_mfma_f32_16x16x32_bf16 v[86:89], v[174:177], v[224:227], v[86:89]
	v_mfma_f32_16x16x32_bf16 v[82:85], v[186:189], v[224:227], v[82:85]
	v_mfma_f32_16x16x32_bf16 v[70:73], v[174:177], v[232:235], v[70:73]
	v_mfma_f32_16x16x32_bf16 v[66:69], v[186:189], v[232:235], v[66:69]
	v_mfma_f32_16x16x32_bf16 v[118:121], v[182:185], v[212:215], v[118:121]
	v_mfma_f32_16x16x32_bf16 v[114:117], v[204:207], v[212:215], v[114:117]
	v_mfma_f32_16x16x32_bf16 v[102:105], v[182:185], v[220:223], v[102:105]
	v_mfma_f32_16x16x32_bf16 v[98:101], v[204:207], v[220:223], v[98:101]
	v_mfma_f32_16x16x32_bf16 v[86:89], v[182:185], v[228:231], v[86:89]
	v_mfma_f32_16x16x32_bf16 v[82:85], v[204:207], v[228:231], v[82:85]
	v_mfma_f32_16x16x32_bf16 v[70:73], v[182:185], v[236:239], v[70:73]
	v_mfma_f32_16x16x32_bf16 v[66:69], v[204:207], v[236:239], v[66:69]
	s_setprio 0
	s_barrier
	s_add_i32 s20, s50, s34
	v_lshl_add_u64 v[140:141], s[24:25], 0, v[0:1]
	s_mov_b32 m0, s20
	ds_read_b128 v[208:211], v145 offset:16384
	ds_read_b128 v[212:215], v145 offset:17408
	ds_read_b128 v[216:219], v145 offset:18432
	ds_read_b128 v[220:223], v145 offset:19456
	ds_read_b128 v[224:227], v145 offset:20480
	ds_read_b128 v[228:231], v145 offset:21504
	ds_read_b128 v[232:235], v145 offset:22528
	ds_read_b128 v[236:239], v145 offset:23552
	global_load_lds_dwordx4 v[140:141], off
	s_add_i32 m0, s20, 0x2000
	s_add_u32 s20, s24, 0xb0000
	v_lshl_add_u64 v[178:179], s[24:25], 0, v[130:131]
	s_addc_u32 s21, s25, 0
	s_add_i32 s50, s51, s34
	global_load_lds_dwordx4 v[178:179], off
	v_lshl_add_u64 v[190:191], s[20:21], 0, v[0:1]
	s_mov_b32 m0, s50
	v_lshl_add_u64 v[240:241], s[26:27], 0, v[130:131]
	global_load_lds_dwordx4 v[190:191], off
	v_lshl_add_u64 v[190:191], s[20:21], 0, v[130:131]
	s_add_i32 m0, s50, 0x2000
	s_nop 0
	global_load_lds_dwordx4 v[190:191], off
	v_lshl_add_u64 v[190:191], s[26:27], 0, v[0:1]
	s_mov_b32 m0, s35
	s_nop 0
	global_load_lds_dwordx4 v[190:191], off
	s_mov_b32 m0, s36
	s_nop 0
	global_load_lds_dwordx4 v[240:241], off
	s_waitcnt vmcnt(8)
	s_waitcnt lgkmcnt(0)
	s_barrier
	s_setprio 1
	s_waitcnt lgkmcnt(0)
	v_mfma_f32_16x16x32_bf16 v[62:65], v[136:139], v[208:211], v[62:65]
	v_mfma_f32_16x16x32_bf16 v[58:61], v[166:169], v[208:211], v[58:61]
	v_mfma_f32_16x16x32_bf16 v[46:49], v[136:139], v[216:219], v[46:49]
	v_mfma_f32_16x16x32_bf16 v[42:45], v[166:169], v[216:219], v[42:45]
	v_mfma_f32_16x16x32_bf16 v[30:33], v[136:139], v[224:227], v[30:33]
	v_mfma_f32_16x16x32_bf16 v[26:29], v[166:169], v[224:227], v[26:29]
	v_mfma_f32_16x16x32_bf16 v[14:17], v[136:139], v[232:235], v[14:17]
	v_mfma_f32_16x16x32_bf16 v[10:13], v[166:169], v[232:235], v[10:13]
	v_mfma_f32_16x16x32_bf16 v[62:65], v[162:165], v[212:215], v[62:65]
	v_mfma_f32_16x16x32_bf16 v[58:61], v[170:173], v[212:215], v[58:61]
	v_mfma_f32_16x16x32_bf16 v[46:49], v[162:165], v[220:223], v[46:49]
	v_mfma_f32_16x16x32_bf16 v[42:45], v[170:173], v[220:223], v[42:45]
	v_mfma_f32_16x16x32_bf16 v[30:33], v[162:165], v[228:231], v[30:33]
	v_mfma_f32_16x16x32_bf16 v[26:29], v[170:173], v[228:231], v[26:29]
	v_mfma_f32_16x16x32_bf16 v[14:17], v[162:165], v[236:239], v[14:17]
	v_mfma_f32_16x16x32_bf16 v[10:13], v[170:173], v[236:239], v[10:13]
	s_setprio 0
	s_setprio 1
	v_mfma_f32_16x16x32_bf16 v[54:57], v[174:177], v[208:211], v[54:57]
	v_mfma_f32_16x16x32_bf16 v[50:53], v[186:189], v[208:211], v[50:53]
	v_mfma_f32_16x16x32_bf16 v[38:41], v[174:177], v[216:219], v[38:41]
	v_mfma_f32_16x16x32_bf16 v[34:37], v[186:189], v[216:219], v[34:37]
	v_mfma_f32_16x16x32_bf16 v[22:25], v[174:177], v[224:227], v[22:25]
	v_mfma_f32_16x16x32_bf16 v[18:21], v[186:189], v[224:227], v[18:21]
	v_mfma_f32_16x16x32_bf16 v[6:9], v[174:177], v[232:235], v[6:9]
	v_mfma_f32_16x16x32_bf16 v[2:5], v[186:189], v[232:235], v[2:5]
	v_mfma_f32_16x16x32_bf16 v[54:57], v[182:185], v[212:215], v[54:57]
	v_mfma_f32_16x16x32_bf16 v[50:53], v[204:207], v[212:215], v[50:53]
	v_mfma_f32_16x16x32_bf16 v[38:41], v[182:185], v[220:223], v[38:41]
	v_mfma_f32_16x16x32_bf16 v[34:37], v[204:207], v[220:223], v[34:37]
	v_mfma_f32_16x16x32_bf16 v[22:25], v[182:185], v[228:231], v[22:25]
	v_mfma_f32_16x16x32_bf16 v[18:21], v[204:207], v[228:231], v[18:21]
	v_mfma_f32_16x16x32_bf16 v[6:9], v[182:185], v[236:239], v[6:9]
	v_mfma_f32_16x16x32_bf16 v[2:5], v[204:207], v[236:239], v[2:5]
	s_setprio 0
	s_barrier
	s_add_i32 s50, 0, 0x18000
	v_add_u32_e32 v160, s50, v143
	s_add_i32 s51, 0, 0x1c000
	ds_read_b128 v[136:139], v160
	ds_read_b128 v[162:165], v160 offset:1024
	ds_read_b128 v[166:169], v160 offset:2048
	ds_read_b128 v[170:173], v160 offset:3072
	v_add_u32_e32 v160, s51, v143
	ds_read_b128 v[174:177], v160
	ds_read_b128 v[182:185], v160 offset:1024
	ds_read_b128 v[186:189], v160 offset:2048
	ds_read_b128 v[204:207], v160 offset:3072
	s_add_u32 s20, s26, 0xb0000
	s_addc_u32 s21, s27, 0
	s_mov_b32 m0, s37
	v_lshl_add_u64 v[242:243], s[20:21], 0, v[0:1]
	ds_read_b128 v[208:211], v145 offset:32768
	ds_read_b128 v[212:215], v145 offset:33792
	ds_read_b128 v[216:219], v145 offset:34816
	ds_read_b128 v[220:223], v145 offset:35840
	ds_read_b128 v[224:227], v145 offset:36864
	ds_read_b128 v[228:231], v145 offset:37888
	ds_read_b128 v[232:235], v145 offset:38912
	ds_read_b128 v[236:239], v145 offset:39936
	global_load_lds_dwordx4 v[242:243], off
	v_lshl_add_u64 v[242:243], s[20:21], 0, v[130:131]
	s_mov_b32 m0, s38
	s_nop 0
	global_load_lds_dwordx4 v[242:243], off
	s_waitcnt vmcnt(8)
	s_waitcnt lgkmcnt(0)
	s_barrier
	s_setprio 1
	s_waitcnt lgkmcnt(0)
	v_mfma_f32_16x16x32_bf16 v[126:129], v[136:139], v[208:211], v[126:129]
	v_mfma_f32_16x16x32_bf16 v[122:125], v[166:169], v[208:211], v[122:125]
	v_mfma_f32_16x16x32_bf16 v[110:113], v[136:139], v[216:219], v[110:113]
	v_mfma_f32_16x16x32_bf16 v[106:109], v[166:169], v[216:219], v[106:109]
	v_mfma_f32_16x16x32_bf16 v[94:97], v[136:139], v[224:227], v[94:97]
	v_mfma_f32_16x16x32_bf16 v[90:93], v[166:169], v[224:227], v[90:93]
	v_mfma_f32_16x16x32_bf16 v[78:81], v[136:139], v[232:235], v[78:81]
	v_mfma_f32_16x16x32_bf16 v[74:77], v[166:169], v[232:235], v[74:77]
	v_mfma_f32_16x16x32_bf16 v[126:129], v[162:165], v[212:215], v[126:129]
	v_mfma_f32_16x16x32_bf16 v[122:125], v[170:173], v[212:215], v[122:125]
	v_mfma_f32_16x16x32_bf16 v[110:113], v[162:165], v[220:223], v[110:113]
	v_mfma_f32_16x16x32_bf16 v[106:109], v[170:173], v[220:223], v[106:109]
	v_mfma_f32_16x16x32_bf16 v[94:97], v[162:165], v[228:231], v[94:97]
	v_mfma_f32_16x16x32_bf16 v[90:93], v[170:173], v[228:231], v[90:93]
	v_mfma_f32_16x16x32_bf16 v[78:81], v[162:165], v[236:239], v[78:81]
	v_mfma_f32_16x16x32_bf16 v[74:77], v[170:173], v[236:239], v[74:77]
	s_setprio 0
	s_setprio 1
	v_mfma_f32_16x16x32_bf16 v[118:121], v[174:177], v[208:211], v[118:121]
	v_mfma_f32_16x16x32_bf16 v[114:117], v[186:189], v[208:211], v[114:117]
	v_mfma_f32_16x16x32_bf16 v[102:105], v[174:177], v[216:219], v[102:105]
	v_mfma_f32_16x16x32_bf16 v[98:101], v[186:189], v[216:219], v[98:101]
	v_mfma_f32_16x16x32_bf16 v[86:89], v[174:177], v[224:227], v[86:89]
	v_mfma_f32_16x16x32_bf16 v[82:85], v[186:189], v[224:227], v[82:85]
	v_mfma_f32_16x16x32_bf16 v[70:73], v[174:177], v[232:235], v[70:73]
	v_mfma_f32_16x16x32_bf16 v[66:69], v[186:189], v[232:235], v[66:69]
	v_mfma_f32_16x16x32_bf16 v[118:121], v[182:185], v[212:215], v[118:121]
	v_mfma_f32_16x16x32_bf16 v[114:117], v[204:207], v[212:215], v[114:117]
	v_mfma_f32_16x16x32_bf16 v[102:105], v[182:185], v[220:223], v[102:105]
	v_mfma_f32_16x16x32_bf16 v[98:101], v[204:207], v[220:223], v[98:101]
	v_mfma_f32_16x16x32_bf16 v[86:89], v[182:185], v[228:231], v[86:89]
	v_mfma_f32_16x16x32_bf16 v[82:85], v[204:207], v[228:231], v[82:85]
	v_mfma_f32_16x16x32_bf16 v[70:73], v[182:185], v[236:239], v[70:73]
	v_mfma_f32_16x16x32_bf16 v[66:69], v[204:207], v[236:239], v[66:69]
	s_setprio 0
	s_barrier
	s_add_i32 s20, s50, s34
	v_lshl_add_u64 v[140:141], v[140:141], 0, s[80:81]
	s_mov_b32 m0, s20
	ds_read_b128 v[208:211], v145 offset:49152
	ds_read_b128 v[212:215], v145 offset:50176
	ds_read_b128 v[216:219], v145 offset:51200
	ds_read_b128 v[220:223], v145 offset:52224
	ds_read_b128 v[224:227], v145 offset:53248
	ds_read_b128 v[228:231], v145 offset:54272
	ds_read_b128 v[232:235], v145 offset:55296
	ds_read_b128 v[236:239], v145 offset:56320
	global_load_lds_dwordx4 v[140:141], off
	s_add_i32 m0, s20, 0x2000
	s_add_u32 s20, s24, 0xb0080
	v_lshl_add_u64 v[140:141], v[178:179], 0, s[80:81]
	s_addc_u32 s21, s25, 0
	s_add_i32 s24, s51, s34
	global_load_lds_dwordx4 v[140:141], off
	v_lshl_add_u64 v[140:141], s[20:21], 0, v[0:1]
	s_mov_b32 m0, s24
	s_nop 0
	global_load_lds_dwordx4 v[140:141], off
	v_lshl_add_u64 v[140:141], s[20:21], 0, v[130:131]
	s_add_i32 m0, s24, 0x2000
	s_nop 0
	global_load_lds_dwordx4 v[140:141], off
	v_lshl_add_u64 v[140:141], v[190:191], 0, s[80:81]
	s_mov_b32 m0, s40
	s_nop 0
	global_load_lds_dwordx4 v[140:141], off
	v_lshl_add_u64 v[140:141], v[240:241], 0, s[80:81]
	s_mov_b32 m0, s41
	s_nop 0
	global_load_lds_dwordx4 v[140:141], off
	s_waitcnt vmcnt(8)
	s_waitcnt lgkmcnt(0)
	s_barrier
	s_setprio 1
	s_waitcnt lgkmcnt(0)
	v_mfma_f32_16x16x32_bf16 v[62:65], v[136:139], v[208:211], v[62:65]
	v_mfma_f32_16x16x32_bf16 v[58:61], v[166:169], v[208:211], v[58:61]
	v_mfma_f32_16x16x32_bf16 v[46:49], v[136:139], v[216:219], v[46:49]
	v_mfma_f32_16x16x32_bf16 v[42:45], v[166:169], v[216:219], v[42:45]
	v_mfma_f32_16x16x32_bf16 v[30:33], v[136:139], v[224:227], v[30:33]
	v_mfma_f32_16x16x32_bf16 v[26:29], v[166:169], v[224:227], v[26:29]
	v_mfma_f32_16x16x32_bf16 v[14:17], v[136:139], v[232:235], v[14:17]
	v_mfma_f32_16x16x32_bf16 v[10:13], v[166:169], v[232:235], v[10:13]
	v_mfma_f32_16x16x32_bf16 v[62:65], v[162:165], v[212:215], v[62:65]
	v_mfma_f32_16x16x32_bf16 v[58:61], v[170:173], v[212:215], v[58:61]
	v_mfma_f32_16x16x32_bf16 v[46:49], v[162:165], v[220:223], v[46:49]
	v_mfma_f32_16x16x32_bf16 v[42:45], v[170:173], v[220:223], v[42:45]
	v_mfma_f32_16x16x32_bf16 v[30:33], v[162:165], v[228:231], v[30:33]
	v_mfma_f32_16x16x32_bf16 v[26:29], v[170:173], v[228:231], v[26:29]
	v_mfma_f32_16x16x32_bf16 v[14:17], v[162:165], v[236:239], v[14:17]
	v_mfma_f32_16x16x32_bf16 v[10:13], v[170:173], v[236:239], v[10:13]
	s_setprio 0
	s_setprio 1
	v_mfma_f32_16x16x32_bf16 v[54:57], v[174:177], v[208:211], v[54:57]
	v_mfma_f32_16x16x32_bf16 v[50:53], v[186:189], v[208:211], v[50:53]
	v_mfma_f32_16x16x32_bf16 v[38:41], v[174:177], v[216:219], v[38:41]
	v_mfma_f32_16x16x32_bf16 v[34:37], v[186:189], v[216:219], v[34:37]
	v_mfma_f32_16x16x32_bf16 v[22:25], v[174:177], v[224:227], v[22:25]
	v_mfma_f32_16x16x32_bf16 v[18:21], v[186:189], v[224:227], v[18:21]
	v_mfma_f32_16x16x32_bf16 v[6:9], v[174:177], v[232:235], v[6:9]
	v_mfma_f32_16x16x32_bf16 v[2:5], v[186:189], v[232:235], v[2:5]
	v_mfma_f32_16x16x32_bf16 v[54:57], v[182:185], v[212:215], v[54:57]
	v_mfma_f32_16x16x32_bf16 v[50:53], v[204:207], v[212:215], v[50:53]
	v_mfma_f32_16x16x32_bf16 v[38:41], v[182:185], v[220:223], v[38:41]
	v_mfma_f32_16x16x32_bf16 v[34:37], v[204:207], v[220:223], v[34:37]
	v_mfma_f32_16x16x32_bf16 v[22:25], v[182:185], v[228:231], v[22:25]
	v_mfma_f32_16x16x32_bf16 v[18:21], v[204:207], v[228:231], v[18:21]
	v_mfma_f32_16x16x32_bf16 v[6:9], v[182:185], v[236:239], v[6:9]
	v_mfma_f32_16x16x32_bf16 v[2:5], v[204:207], v[236:239], v[2:5]
	s_add_i32 s49, s49, 2
	s_add_u32 s47, s47, 0x100
	s_addc_u32 s48, s48, 0
	s_cmp_gt_u32 s49, 41
	s_mov_b64 s[20:21], s[22:23]
	s_setprio 0
	s_barrier
	s_cbranch_scc0 .LBB0_310
	s_and_b64 vcc, exec, s[16:17]
	s_cbranch_vccz .LBB0_313
	s_barrier

.LBB0_394:
	s_add_u32 s22, s10, 0xfffc0080
	s_addc_u32 s23, s11, -1
	s_add_i32 s47, 0, 0x10000
	s_cmp_eq_u32 s46, 12
	s_cselect_b32 s25, s17, s23
	s_cselect_b32 s24, s42, s22
	v_add_u32_e32 v163, s47, v145
	s_cselect_b32 s23, s15, s45
	s_cselect_b32 s22, s43, s44
	s_add_i32 s50, 0, 0x14000
	ds_read_b128 v[140:143], v163
	ds_read_b128 v[164:167], v163 offset:1024
	ds_read_b128 v[168:171], v163 offset:2048
	ds_read_b128 v[172:175], v163 offset:3072
	v_add_u32_e32 v163, s50, v145
	ds_read_b128 v[176:179], v163
	ds_read_b128 v[182:185], v163 offset:1024
	ds_read_b128 v[186:189], v163 offset:2048
	ds_read_b128 v[204:207], v163 offset:3072
	v_lshl_add_u64 v[190:191], s[10:11], 0, v[136:137]
	s_add_i32 m0, s31, 0xc000
	ds_read_b128 v[208:211], v162
	ds_read_b128 v[212:215], v162 offset:1024
	ds_read_b128 v[216:219], v162 offset:2048
	ds_read_b128 v[220:223], v162 offset:3072
	ds_read_b128 v[224:227], v162 offset:4096
	ds_read_b128 v[228:231], v162 offset:5120
	ds_read_b128 v[232:235], v162 offset:6144
	ds_read_b128 v[236:239], v162 offset:7168
	global_load_lds_dwordx4 v[190:191], off
	v_lshl_add_u64 v[190:191], s[10:11], 0, v[138:139]
	s_add_i32 m0, s31, 0xe000
	s_nop 0
	global_load_lds_dwordx4 v[190:191], off
	s_waitcnt vmcnt(8)
	s_waitcnt lgkmcnt(0)
	s_barrier
	s_setprio 1
	s_waitcnt lgkmcnt(0)
	v_mfma_f32_16x16x32_bf16 v[126:129], v[140:143], v[208:211], v[126:129]
	v_mfma_f32_16x16x32_bf16 v[122:125], v[168:171], v[208:211], v[122:125]
	v_mfma_f32_16x16x32_bf16 v[110:113], v[140:143], v[216:219], v[110:113]
	v_mfma_f32_16x16x32_bf16 v[106:109], v[168:171], v[216:219], v[106:109]
	v_mfma_f32_16x16x32_bf16 v[94:97], v[140:143], v[224:227], v[94:97]
	v_mfma_f32_16x16x32_bf16 v[90:93], v[168:171], v[224:227], v[90:93]
	v_mfma_f32_16x16x32_bf16 v[78:81], v[140:143], v[232:235], v[78:81]
	v_mfma_f32_16x16x32_bf16 v[74:77], v[168:171], v[232:235], v[74:77]
	v_mfma_f32_16x16x32_bf16 v[126:129], v[164:167], v[212:215], v[126:129]
	v_mfma_f32_16x16x32_bf16 v[122:125], v[172:175], v[212:215], v[122:125]
	v_mfma_f32_16x16x32_bf16 v[110:113], v[164:167], v[220:223], v[110:113]
	v_mfma_f32_16x16x32_bf16 v[106:109], v[172:175], v[220:223], v[106:109]
	v_mfma_f32_16x16x32_bf16 v[94:97], v[164:167], v[228:231], v[94:97]
	v_mfma_f32_16x16x32_bf16 v[90:93], v[172:175], v[228:231], v[90:93]
	v_mfma_f32_16x16x32_bf16 v[78:81], v[164:167], v[236:239], v[78:81]
	v_mfma_f32_16x16x32_bf16 v[74:77], v[172:175], v[236:239], v[74:77]
	s_setprio 0
	s_setprio 1
	v_mfma_f32_16x16x32_bf16 v[118:121], v[176:179], v[208:211], v[118:121]
	v_mfma_f32_16x16x32_bf16 v[114:117], v[186:189], v[208:211], v[114:117]
	v_mfma_f32_16x16x32_bf16 v[102:105], v[176:179], v[216:219], v[102:105]
	v_mfma_f32_16x16x32_bf16 v[98:101], v[186:189], v[216:219], v[98:101]
	v_mfma_f32_16x16x32_bf16 v[86:89], v[176:179], v[224:227], v[86:89]
	v_mfma_f32_16x16x32_bf16 v[82:85], v[186:189], v[224:227], v[82:85]
	v_mfma_f32_16x16x32_bf16 v[70:73], v[176:179], v[232:235], v[70:73]
	v_mfma_f32_16x16x32_bf16 v[66:69], v[186:189], v[232:235], v[66:69]
	v_mfma_f32_16x16x32_bf16 v[118:121], v[182:185], v[212:215], v[118:121]
	v_mfma_f32_16x16x32_bf16 v[114:117], v[204:207], v[212:215], v[114:117]
	v_mfma_f32_16x16x32_bf16 v[102:105], v[182:185], v[220:223], v[102:105]
	v_mfma_f32_16x16x32_bf16 v[98:101], v[204:207], v[220:223], v[98:101]
	v_mfma_f32_16x16x32_bf16 v[86:89], v[182:185], v[228:231], v[86:89]
	v_mfma_f32_16x16x32_bf16 v[82:85], v[204:207], v[228:231], v[82:85]
	v_mfma_f32_16x16x32_bf16 v[70:73], v[182:185], v[236:239], v[70:73]
	v_mfma_f32_16x16x32_bf16 v[66:69], v[204:207], v[236:239], v[66:69]
	s_setprio 0
	s_barrier
	s_add_i32 s47, s47, s30
	v_lshl_add_u64 v[190:191], s[22:23], 0, v[0:1]
	s_mov_b32 m0, s47
	ds_read_b128 v[208:211], v162 offset:16384
	ds_read_b128 v[212:215], v162 offset:17408
	ds_read_b128 v[216:219], v162 offset:18432
	ds_read_b128 v[220:223], v162 offset:19456
	ds_read_b128 v[224:227], v162 offset:20480
	ds_read_b128 v[228:231], v162 offset:21504
	ds_read_b128 v[232:235], v162 offset:22528
	ds_read_b128 v[236:239], v162 offset:23552
	global_load_lds_dwordx4 v[190:191], off
	s_add_i32 m0, s47, 0x2000
	s_add_u32 s48, s22, 0x40000
	v_lshl_add_u64 v[240:241], s[22:23], 0, v[130:131]
	s_addc_u32 s49, s23, 0
	s_add_i32 s47, s50, s30
	global_load_lds_dwordx4 v[240:241], off
	v_lshl_add_u64 v[242:243], s[48:49], 0, v[0:1]
	s_mov_b32 m0, s47
	v_lshl_add_u64 v[244:245], s[24:25], 0, v[132:133]
	global_load_lds_dwordx4 v[242:243], off
	v_lshl_add_u64 v[242:243], s[48:49], 0, v[130:131]
	s_add_i32 m0, s47, 0x2000
	s_nop 0
	global_load_lds_dwordx4 v[242:243], off
	v_lshl_add_u64 v[242:243], s[24:25], 0, v[134:135]
	s_mov_b32 m0, s31
	s_nop 0
	global_load_lds_dwordx4 v[242:243], off
	s_mov_b32 m0, s34
	s_nop 0
	global_load_lds_dwordx4 v[244:245], off
	s_waitcnt vmcnt(8)
	s_waitcnt lgkmcnt(0)
	s_barrier
	s_setprio 1
	s_waitcnt lgkmcnt(0)
	v_mfma_f32_16x16x32_bf16 v[62:65], v[140:143], v[208:211], v[62:65]
	v_mfma_f32_16x16x32_bf16 v[58:61], v[168:171], v[208:211], v[58:61]
	v_mfma_f32_16x16x32_bf16 v[46:49], v[140:143], v[216:219], v[46:49]
	v_mfma_f32_16x16x32_bf16 v[42:45], v[168:171], v[216:219], v[42:45]
	v_mfma_f32_16x16x32_bf16 v[30:33], v[140:143], v[224:227], v[30:33]
	v_mfma_f32_16x16x32_bf16 v[26:29], v[168:171], v[224:227], v[26:29]
	v_mfma_f32_16x16x32_bf16 v[14:17], v[140:143], v[232:235], v[14:17]
	v_mfma_f32_16x16x32_bf16 v[10:13], v[168:171], v[232:235], v[10:13]
	v_mfma_f32_16x16x32_bf16 v[62:65], v[164:167], v[212:215], v[62:65]
	v_mfma_f32_16x16x32_bf16 v[58:61], v[172:175], v[212:215], v[58:61]
	v_mfma_f32_16x16x32_bf16 v[46:49], v[164:167], v[220:223], v[46:49]
	v_mfma_f32_16x16x32_bf16 v[42:45], v[172:175], v[220:223], v[42:45]
	v_mfma_f32_16x16x32_bf16 v[30:33], v[164:167], v[228:231], v[30:33]
	v_mfma_f32_16x16x32_bf16 v[26:29], v[172:175], v[228:231], v[26:29]
	v_mfma_f32_16x16x32_bf16 v[14:17], v[164:167], v[236:239], v[14:17]
	v_mfma_f32_16x16x32_bf16 v[10:13], v[172:175], v[236:239], v[10:13]
	s_setprio 0
	s_setprio 1
	v_mfma_f32_16x16x32_bf16 v[54:57], v[176:179], v[208:211], v[54:57]
	v_mfma_f32_16x16x32_bf16 v[50:53], v[186:189], v[208:211], v[50:53]
	v_mfma_f32_16x16x32_bf16 v[38:41], v[176:179], v[216:219], v[38:41]
	v_mfma_f32_16x16x32_bf16 v[34:37], v[186:189], v[216:219], v[34:37]
	v_mfma_f32_16x16x32_bf16 v[22:25], v[176:179], v[224:227], v[22:25]
	v_mfma_f32_16x16x32_bf16 v[18:21], v[186:189], v[224:227], v[18:21]
	v_mfma_f32_16x16x32_bf16 v[6:9], v[176:179], v[232:235], v[6:9]
	v_mfma_f32_16x16x32_bf16 v[2:5], v[186:189], v[232:235], v[2:5]
	v_mfma_f32_16x16x32_bf16 v[54:57], v[182:185], v[212:215], v[54:57]
	v_mfma_f32_16x16x32_bf16 v[50:53], v[204:207], v[212:215], v[50:53]
	v_mfma_f32_16x16x32_bf16 v[38:41], v[182:185], v[220:223], v[38:41]
	v_mfma_f32_16x16x32_bf16 v[34:37], v[204:207], v[220:223], v[34:37]
	v_mfma_f32_16x16x32_bf16 v[22:25], v[182:185], v[228:231], v[22:25]
	v_mfma_f32_16x16x32_bf16 v[18:21], v[204:207], v[228:231], v[18:21]
	v_mfma_f32_16x16x32_bf16 v[6:9], v[182:185], v[236:239], v[6:9]
	v_mfma_f32_16x16x32_bf16 v[2:5], v[204:207], v[236:239], v[2:5]
	s_setprio 0
	s_barrier
	s_add_i32 s47, 0, 0x18000
	v_add_u32_e32 v163, s47, v145
	s_add_i32 s48, 0, 0x1c000
	ds_read_b128 v[140:143], v163
	ds_read_b128 v[164:167], v163 offset:1024
	ds_read_b128 v[168:171], v163 offset:2048
	ds_read_b128 v[172:175], v163 offset:3072
	v_add_u32_e32 v163, s48, v145
	ds_read_b128 v[176:179], v163
	ds_read_b128 v[182:185], v163 offset:1024
	ds_read_b128 v[186:189], v163 offset:2048
	ds_read_b128 v[204:207], v163 offset:3072
	s_add_u32 s24, s24, 0x40000
	s_addc_u32 s25, s25, 0
	s_mov_b32 m0, s35
	v_lshl_add_u64 v[246:247], s[24:25], 0, v[134:135]
	ds_read_b128 v[208:211], v162 offset:32768
	ds_read_b128 v[212:215], v162 offset:33792
	ds_read_b128 v[216:219], v162 offset:34816
	ds_read_b128 v[220:223], v162 offset:35840
	ds_read_b128 v[224:227], v162 offset:36864
	ds_read_b128 v[228:231], v162 offset:37888
	ds_read_b128 v[232:235], v162 offset:38912
	ds_read_b128 v[236:239], v162 offset:39936
	global_load_lds_dwordx4 v[246:247], off
	v_lshl_add_u64 v[246:247], s[24:25], 0, v[132:133]
	s_mov_b32 m0, s36
	s_nop 0
	global_load_lds_dwordx4 v[246:247], off
	s_waitcnt vmcnt(8)
	s_waitcnt lgkmcnt(0)
	s_barrier
	s_setprio 1
	s_waitcnt lgkmcnt(0)
	v_mfma_f32_16x16x32_bf16 v[126:129], v[140:143], v[208:211], v[126:129]
	v_mfma_f32_16x16x32_bf16 v[122:125], v[168:171], v[208:211], v[122:125]
	v_mfma_f32_16x16x32_bf16 v[110:113], v[140:143], v[216:219], v[110:113]
	v_mfma_f32_16x16x32_bf16 v[106:109], v[168:171], v[216:219], v[106:109]
	v_mfma_f32_16x16x32_bf16 v[94:97], v[140:143], v[224:227], v[94:97]
	v_mfma_f32_16x16x32_bf16 v[90:93], v[168:171], v[224:227], v[90:93]
	v_mfma_f32_16x16x32_bf16 v[78:81], v[140:143], v[232:235], v[78:81]
	v_mfma_f32_16x16x32_bf16 v[74:77], v[168:171], v[232:235], v[74:77]
	v_mfma_f32_16x16x32_bf16 v[126:129], v[164:167], v[212:215], v[126:129]
	v_mfma_f32_16x16x32_bf16 v[122:125], v[172:175], v[212:215], v[122:125]
	v_mfma_f32_16x16x32_bf16 v[110:113], v[164:167], v[220:223], v[110:113]
	v_mfma_f32_16x16x32_bf16 v[106:109], v[172:175], v[220:223], v[106:109]
	v_mfma_f32_16x16x32_bf16 v[94:97], v[164:167], v[228:231], v[94:97]
	v_mfma_f32_16x16x32_bf16 v[90:93], v[172:175], v[228:231], v[90:93]
	v_mfma_f32_16x16x32_bf16 v[78:81], v[164:167], v[236:239], v[78:81]
	v_mfma_f32_16x16x32_bf16 v[74:77], v[172:175], v[236:239], v[74:77]
	s_setprio 0
	s_setprio 1
	v_mfma_f32_16x16x32_bf16 v[118:121], v[176:179], v[208:211], v[118:121]
	v_mfma_f32_16x16x32_bf16 v[114:117], v[186:189], v[208:211], v[114:117]
	v_mfma_f32_16x16x32_bf16 v[102:105], v[176:179], v[216:219], v[102:105]
	v_mfma_f32_16x16x32_bf16 v[98:101], v[186:189], v[216:219], v[98:101]
	v_mfma_f32_16x16x32_bf16 v[86:89], v[176:179], v[224:227], v[86:89]
	v_mfma_f32_16x16x32_bf16 v[82:85], v[186:189], v[224:227], v[82:85]
	v_mfma_f32_16x16x32_bf16 v[70:73], v[176:179], v[232:235], v[70:73]
	v_mfma_f32_16x16x32_bf16 v[66:69], v[186:189], v[232:235], v[66:69]
	v_mfma_f32_16x16x32_bf16 v[118:121], v[182:185], v[212:215], v[118:121]
	v_mfma_f32_16x16x32_bf16 v[114:117], v[204:207], v[212:215], v[114:117]
	v_mfma_f32_16x16x32_bf16 v[102:105], v[182:185], v[220:223], v[102:105]
	v_mfma_f32_16x16x32_bf16 v[98:101], v[204:207], v[220:223], v[98:101]
	v_mfma_f32_16x16x32_bf16 v[86:89], v[182:185], v[228:231], v[86:89]
	v_mfma_f32_16x16x32_bf16 v[82:85], v[204:207], v[228:231], v[82:85]
	v_mfma_f32_16x16x32_bf16 v[70:73], v[182:185], v[236:239], v[70:73]
	v_mfma_f32_16x16x32_bf16 v[66:69], v[204:207], v[236:239], v[66:69]
	s_setprio 0
	s_barrier
	s_add_i32 s24, s47, s30
	v_lshl_add_u64 v[190:191], v[190:191], 0, s[80:81]
	s_mov_b32 m0, s24
	ds_read_b128 v[208:211], v162 offset:49152
	ds_read_b128 v[212:215], v162 offset:50176
	ds_read_b128 v[216:219], v162 offset:51200
	ds_read_b128 v[220:223], v162 offset:52224
	ds_read_b128 v[224:227], v162 offset:53248
	ds_read_b128 v[228:231], v162 offset:54272
	ds_read_b128 v[232:235], v162 offset:55296
	ds_read_b128 v[236:239], v162 offset:56320
	global_load_lds_dwordx4 v[190:191], off
	s_add_i32 m0, s24, 0x2000
	s_add_u32 s22, s22, 0x40080
	v_lshl_add_u64 v[190:191], v[240:241], 0, s[80:81]
	s_addc_u32 s23, s23, 0
	s_add_i32 s24, s48, s30
	global_load_lds_dwordx4 v[190:191], off
	v_lshl_add_u64 v[190:191], s[22:23], 0, v[0:1]
	s_mov_b32 m0, s24
	s_nop 0
	global_load_lds_dwordx4 v[190:191], off
	v_lshl_add_u64 v[190:191], s[22:23], 0, v[130:131]
	s_add_i32 m0, s24, 0x2000
	s_nop 0
	global_load_lds_dwordx4 v[190:191], off
	v_lshl_add_u64 v[190:191], v[242:243], 0, s[80:81]
	s_mov_b32 m0, s37
	s_nop 0
	global_load_lds_dwordx4 v[190:191], off
	v_lshl_add_u64 v[190:191], v[244:245], 0, s[80:81]
	s_mov_b32 m0, s38
	s_nop 0
	global_load_lds_dwordx4 v[190:191], off
	s_waitcnt vmcnt(8)
	s_waitcnt lgkmcnt(0)
	s_barrier
	s_setprio 1
	s_waitcnt lgkmcnt(0)
	v_mfma_f32_16x16x32_bf16 v[62:65], v[140:143], v[208:211], v[62:65]
	v_mfma_f32_16x16x32_bf16 v[58:61], v[168:171], v[208:211], v[58:61]
	v_mfma_f32_16x16x32_bf16 v[46:49], v[140:143], v[216:219], v[46:49]
	v_mfma_f32_16x16x32_bf16 v[42:45], v[168:171], v[216:219], v[42:45]
	v_mfma_f32_16x16x32_bf16 v[30:33], v[140:143], v[224:227], v[30:33]
	v_mfma_f32_16x16x32_bf16 v[26:29], v[168:171], v[224:227], v[26:29]
	v_mfma_f32_16x16x32_bf16 v[14:17], v[140:143], v[232:235], v[14:17]
	v_mfma_f32_16x16x32_bf16 v[10:13], v[168:171], v[232:235], v[10:13]
	v_mfma_f32_16x16x32_bf16 v[62:65], v[164:167], v[212:215], v[62:65]
	v_mfma_f32_16x16x32_bf16 v[58:61], v[172:175], v[212:215], v[58:61]
	v_mfma_f32_16x16x32_bf16 v[46:49], v[164:167], v[220:223], v[46:49]
	v_mfma_f32_16x16x32_bf16 v[42:45], v[172:175], v[220:223], v[42:45]
	v_mfma_f32_16x16x32_bf16 v[30:33], v[164:167], v[228:231], v[30:33]
	v_mfma_f32_16x16x32_bf16 v[26:29], v[172:175], v[228:231], v[26:29]
	v_mfma_f32_16x16x32_bf16 v[14:17], v[164:167], v[236:239], v[14:17]
	v_mfma_f32_16x16x32_bf16 v[10:13], v[172:175], v[236:239], v[10:13]
	s_setprio 0
	s_setprio 1
	v_mfma_f32_16x16x32_bf16 v[54:57], v[176:179], v[208:211], v[54:57]
	v_mfma_f32_16x16x32_bf16 v[50:53], v[186:189], v[208:211], v[50:53]
	v_mfma_f32_16x16x32_bf16 v[38:41], v[176:179], v[216:219], v[38:41]
	v_mfma_f32_16x16x32_bf16 v[34:37], v[186:189], v[216:219], v[34:37]
	v_mfma_f32_16x16x32_bf16 v[22:25], v[176:179], v[224:227], v[22:25]
	v_mfma_f32_16x16x32_bf16 v[18:21], v[186:189], v[224:227], v[18:21]
	v_mfma_f32_16x16x32_bf16 v[6:9], v[176:179], v[232:235], v[6:9]
	v_mfma_f32_16x16x32_bf16 v[2:5], v[186:189], v[232:235], v[2:5]
	v_mfma_f32_16x16x32_bf16 v[54:57], v[182:185], v[212:215], v[54:57]
	v_mfma_f32_16x16x32_bf16 v[50:53], v[204:207], v[212:215], v[50:53]
	v_mfma_f32_16x16x32_bf16 v[38:41], v[182:185], v[220:223], v[38:41]
	v_mfma_f32_16x16x32_bf16 v[34:37], v[204:207], v[220:223], v[34:37]
	v_mfma_f32_16x16x32_bf16 v[22:25], v[182:185], v[228:231], v[22:25]
	v_mfma_f32_16x16x32_bf16 v[18:21], v[204:207], v[228:231], v[18:21]
	v_mfma_f32_16x16x32_bf16 v[6:9], v[182:185], v[236:239], v[6:9]
	v_mfma_f32_16x16x32_bf16 v[2:5], v[204:207], v[236:239], v[2:5]
	s_add_i32 s46, s46, 2
	s_add_u32 s10, s10, 0x100
	s_addc_u32 s11, s11, 0
	s_add_u32 s44, s44, 0x100
	s_addc_u32 s45, s45, 0
	s_cmp_gt_u32 s46, 13
	s_setprio 0
	s_barrier
	s_cbranch_scc0 .LBB0_394
	s_and_b64 vcc, exec, s[12:13]
	s_cbranch_vccz .LBB0_397
	s_barrier

.LBB0_1402:
	s_add_u32 s20, s18, 0x100
	s_addc_u32 s21, s19, 0
	s_add_i32 s47, 0, 0x10000
	s_cmp_eq_u32 s46, 8
	s_cselect_b32 s25, s11, s21
	s_cselect_b32 s24, s10, s20
	v_add_u32_e32 v144, s47, v162
	s_cselect_b32 s23, s17, s45
	s_cselect_b32 s22, s16, s44
	s_add_i32 s48, 0, 0x14000
	ds_read_b128 v[140:143], v144
	ds_read_b128 v[166:169], v144 offset:1024
	ds_read_b128 v[170:173], v144 offset:2048
	ds_read_b128 v[174:177], v144 offset:3072
	v_add_u32_e32 v144, s48, v162
	ds_read_b128 v[182:185], v144
	ds_read_b128 v[186:189], v144 offset:1024
	ds_read_b128 v[204:207], v144 offset:2048
	ds_read_b128 v[208:211], v144 offset:3072
	v_lshl_add_u64 v[144:145], s[18:19], 0, v[136:137]
	s_add_i32 m0, s31, 0xc000
	ds_read_b128 v[212:215], v164
	ds_read_b128 v[216:219], v164 offset:1024
	ds_read_b128 v[220:223], v164 offset:2048
	ds_read_b128 v[224:227], v164 offset:3072
	ds_read_b128 v[228:231], v164 offset:4096
	ds_read_b128 v[232:235], v164 offset:5120
	ds_read_b128 v[236:239], v164 offset:6144
	ds_read_b128 v[240:243], v164 offset:7168
	global_load_lds_dwordx4 v[144:145], off
	v_lshl_add_u64 v[144:145], s[18:19], 0, v[138:139]
	s_add_i32 m0, s31, 0xe000
	s_nop 0
	global_load_lds_dwordx4 v[144:145], off
	s_waitcnt vmcnt(8)
	s_waitcnt lgkmcnt(0)
	s_barrier
	s_setprio 1
	s_waitcnt lgkmcnt(0)
	v_mfma_f32_16x16x32_bf16 v[126:129], v[140:143], v[212:215], v[126:129]
	v_mfma_f32_16x16x32_bf16 v[122:125], v[170:173], v[212:215], v[122:125]
	v_mfma_f32_16x16x32_bf16 v[110:113], v[140:143], v[220:223], v[110:113]
	v_mfma_f32_16x16x32_bf16 v[106:109], v[170:173], v[220:223], v[106:109]
	v_mfma_f32_16x16x32_bf16 v[94:97], v[140:143], v[228:231], v[94:97]
	v_mfma_f32_16x16x32_bf16 v[90:93], v[170:173], v[228:231], v[90:93]
	v_mfma_f32_16x16x32_bf16 v[78:81], v[140:143], v[236:239], v[78:81]
	v_mfma_f32_16x16x32_bf16 v[74:77], v[170:173], v[236:239], v[74:77]
	v_mfma_f32_16x16x32_bf16 v[126:129], v[166:169], v[216:219], v[126:129]
	v_mfma_f32_16x16x32_bf16 v[122:125], v[174:177], v[216:219], v[122:125]
	v_mfma_f32_16x16x32_bf16 v[110:113], v[166:169], v[224:227], v[110:113]
	v_mfma_f32_16x16x32_bf16 v[106:109], v[174:177], v[224:227], v[106:109]
	v_mfma_f32_16x16x32_bf16 v[94:97], v[166:169], v[232:235], v[94:97]
	v_mfma_f32_16x16x32_bf16 v[90:93], v[174:177], v[232:235], v[90:93]
	v_mfma_f32_16x16x32_bf16 v[78:81], v[166:169], v[240:243], v[78:81]
	v_mfma_f32_16x16x32_bf16 v[74:77], v[174:177], v[240:243], v[74:77]
	s_setprio 0
	s_setprio 1
	v_mfma_f32_16x16x32_bf16 v[118:121], v[182:185], v[212:215], v[118:121]
	v_mfma_f32_16x16x32_bf16 v[114:117], v[204:207], v[212:215], v[114:117]
	v_mfma_f32_16x16x32_bf16 v[102:105], v[182:185], v[220:223], v[102:105]
	v_mfma_f32_16x16x32_bf16 v[98:101], v[204:207], v[220:223], v[98:101]
	v_mfma_f32_16x16x32_bf16 v[86:89], v[182:185], v[228:231], v[86:89]
	v_mfma_f32_16x16x32_bf16 v[82:85], v[204:207], v[228:231], v[82:85]
	v_mfma_f32_16x16x32_bf16 v[70:73], v[182:185], v[236:239], v[70:73]
	v_mfma_f32_16x16x32_bf16 v[66:69], v[204:207], v[236:239], v[66:69]
	v_mfma_f32_16x16x32_bf16 v[118:121], v[186:189], v[216:219], v[118:121]
	v_mfma_f32_16x16x32_bf16 v[114:117], v[208:211], v[216:219], v[114:117]
	v_mfma_f32_16x16x32_bf16 v[102:105], v[186:189], v[224:227], v[102:105]
	v_mfma_f32_16x16x32_bf16 v[98:101], v[208:211], v[224:227], v[98:101]
	v_mfma_f32_16x16x32_bf16 v[86:89], v[186:189], v[232:235], v[86:89]
	v_mfma_f32_16x16x32_bf16 v[82:85], v[208:211], v[232:235], v[82:85]
	v_mfma_f32_16x16x32_bf16 v[70:73], v[186:189], v[240:243], v[70:73]
	v_mfma_f32_16x16x32_bf16 v[66:69], v[208:211], v[240:243], v[66:69]
	s_setprio 0
	s_barrier
	s_add_i32 s18, s47, s30
	v_lshl_add_u64 v[144:145], s[22:23], 0, v[0:1]
	s_mov_b32 m0, s18
	ds_read_b128 v[212:215], v164 offset:16384
	ds_read_b128 v[216:219], v164 offset:17408
	ds_read_b128 v[220:223], v164 offset:18432
	ds_read_b128 v[224:227], v164 offset:19456
	ds_read_b128 v[228:231], v164 offset:20480
	ds_read_b128 v[232:235], v164 offset:21504
	ds_read_b128 v[236:239], v164 offset:22528
	ds_read_b128 v[240:243], v164 offset:23552
	global_load_lds_dwordx4 v[144:145], off
	s_add_i32 m0, s18, 0x2000
	s_add_u32 s18, s22, 0x30000
	v_lshl_add_u64 v[178:179], s[22:23], 0, v[130:131]
	s_addc_u32 s19, s23, 0
	s_add_i32 s47, s48, s30
	global_load_lds_dwordx4 v[178:179], off
	v_lshl_add_u64 v[190:191], s[18:19], 0, v[0:1]
	s_mov_b32 m0, s47
	v_lshl_add_u64 v[244:245], s[24:25], 0, v[132:133]
	global_load_lds_dwordx4 v[190:191], off
	v_lshl_add_u64 v[190:191], s[18:19], 0, v[130:131]
	s_add_i32 m0, s47, 0x2000
	s_nop 0
	global_load_lds_dwordx4 v[190:191], off
	v_lshl_add_u64 v[190:191], s[24:25], 0, v[134:135]
	s_mov_b32 m0, s31
	s_nop 0
	global_load_lds_dwordx4 v[190:191], off
	s_mov_b32 m0, s34
	s_nop 0
	global_load_lds_dwordx4 v[244:245], off
	s_waitcnt vmcnt(8)
	s_waitcnt lgkmcnt(0)
	s_barrier
	s_setprio 1
	s_waitcnt lgkmcnt(0)
	v_mfma_f32_16x16x32_bf16 v[62:65], v[140:143], v[212:215], v[62:65]
	v_mfma_f32_16x16x32_bf16 v[58:61], v[170:173], v[212:215], v[58:61]
	v_mfma_f32_16x16x32_bf16 v[46:49], v[140:143], v[220:223], v[46:49]
	v_mfma_f32_16x16x32_bf16 v[42:45], v[170:173], v[220:223], v[42:45]
	v_mfma_f32_16x16x32_bf16 v[30:33], v[140:143], v[228:231], v[30:33]
	v_mfma_f32_16x16x32_bf16 v[26:29], v[170:173], v[228:231], v[26:29]
	v_mfma_f32_16x16x32_bf16 v[14:17], v[140:143], v[236:239], v[14:17]
	v_mfma_f32_16x16x32_bf16 v[10:13], v[170:173], v[236:239], v[10:13]
	v_mfma_f32_16x16x32_bf16 v[62:65], v[166:169], v[216:219], v[62:65]
	v_mfma_f32_16x16x32_bf16 v[58:61], v[174:177], v[216:219], v[58:61]
	v_mfma_f32_16x16x32_bf16 v[46:49], v[166:169], v[224:227], v[46:49]
	v_mfma_f32_16x16x32_bf16 v[42:45], v[174:177], v[224:227], v[42:45]
	v_mfma_f32_16x16x32_bf16 v[30:33], v[166:169], v[232:235], v[30:33]
	v_mfma_f32_16x16x32_bf16 v[26:29], v[174:177], v[232:235], v[26:29]
	v_mfma_f32_16x16x32_bf16 v[14:17], v[166:169], v[240:243], v[14:17]
	v_mfma_f32_16x16x32_bf16 v[10:13], v[174:177], v[240:243], v[10:13]
	s_setprio 0
	s_setprio 1
	v_mfma_f32_16x16x32_bf16 v[54:57], v[182:185], v[212:215], v[54:57]
	v_mfma_f32_16x16x32_bf16 v[50:53], v[204:207], v[212:215], v[50:53]
	v_mfma_f32_16x16x32_bf16 v[38:41], v[182:185], v[220:223], v[38:41]
	v_mfma_f32_16x16x32_bf16 v[34:37], v[204:207], v[220:223], v[34:37]
	v_mfma_f32_16x16x32_bf16 v[22:25], v[182:185], v[228:231], v[22:25]
	v_mfma_f32_16x16x32_bf16 v[18:21], v[204:207], v[228:231], v[18:21]
	v_mfma_f32_16x16x32_bf16 v[6:9], v[182:185], v[236:239], v[6:9]
	v_mfma_f32_16x16x32_bf16 v[2:5], v[204:207], v[236:239], v[2:5]
	v_mfma_f32_16x16x32_bf16 v[54:57], v[186:189], v[216:219], v[54:57]
	v_mfma_f32_16x16x32_bf16 v[50:53], v[208:211], v[216:219], v[50:53]
	v_mfma_f32_16x16x32_bf16 v[38:41], v[186:189], v[224:227], v[38:41]
	v_mfma_f32_16x16x32_bf16 v[34:37], v[208:211], v[224:227], v[34:37]
	v_mfma_f32_16x16x32_bf16 v[22:25], v[186:189], v[232:235], v[22:25]
	v_mfma_f32_16x16x32_bf16 v[18:21], v[208:211], v[232:235], v[18:21]
	v_mfma_f32_16x16x32_bf16 v[6:9], v[186:189], v[240:243], v[6:9]
	v_mfma_f32_16x16x32_bf16 v[2:5], v[208:211], v[240:243], v[2:5]
	s_setprio 0
	s_barrier
	s_add_i32 s47, 0, 0x18000
	v_add_u32_e32 v165, s47, v162
	s_add_i32 s48, 0, 0x1c000
	ds_read_b128 v[140:143], v165
	ds_read_b128 v[166:169], v165 offset:1024
	ds_read_b128 v[170:173], v165 offset:2048
	ds_read_b128 v[174:177], v165 offset:3072
	v_add_u32_e32 v165, s48, v162
	ds_read_b128 v[182:185], v165
	ds_read_b128 v[186:189], v165 offset:1024
	ds_read_b128 v[204:207], v165 offset:2048
	ds_read_b128 v[208:211], v165 offset:3072
	s_add_u32 s18, s24, 0x30000
	s_addc_u32 s19, s25, 0
	s_mov_b32 m0, s35
	v_lshl_add_u64 v[246:247], s[18:19], 0, v[134:135]
	ds_read_b128 v[212:215], v164 offset:32768
	ds_read_b128 v[216:219], v164 offset:33792
	ds_read_b128 v[220:223], v164 offset:34816
	ds_read_b128 v[224:227], v164 offset:35840
	ds_read_b128 v[228:231], v164 offset:36864
	ds_read_b128 v[232:235], v164 offset:37888
	ds_read_b128 v[236:239], v164 offset:38912
	ds_read_b128 v[240:243], v164 offset:39936
	global_load_lds_dwordx4 v[246:247], off
	v_lshl_add_u64 v[246:247], s[18:19], 0, v[132:133]
	s_mov_b32 m0, s36
	s_nop 0
	global_load_lds_dwordx4 v[246:247], off
	s_waitcnt vmcnt(8)
	s_waitcnt lgkmcnt(0)
	s_barrier
	s_setprio 1
	s_waitcnt lgkmcnt(0)
	v_mfma_f32_16x16x32_bf16 v[126:129], v[140:143], v[212:215], v[126:129]
	v_mfma_f32_16x16x32_bf16 v[122:125], v[170:173], v[212:215], v[122:125]
	v_mfma_f32_16x16x32_bf16 v[110:113], v[140:143], v[220:223], v[110:113]
	v_mfma_f32_16x16x32_bf16 v[106:109], v[170:173], v[220:223], v[106:109]
	v_mfma_f32_16x16x32_bf16 v[94:97], v[140:143], v[228:231], v[94:97]
	v_mfma_f32_16x16x32_bf16 v[90:93], v[170:173], v[228:231], v[90:93]
	v_mfma_f32_16x16x32_bf16 v[78:81], v[140:143], v[236:239], v[78:81]
	v_mfma_f32_16x16x32_bf16 v[74:77], v[170:173], v[236:239], v[74:77]
	v_mfma_f32_16x16x32_bf16 v[126:129], v[166:169], v[216:219], v[126:129]
	v_mfma_f32_16x16x32_bf16 v[122:125], v[174:177], v[216:219], v[122:125]
	v_mfma_f32_16x16x32_bf16 v[110:113], v[166:169], v[224:227], v[110:113]
	v_mfma_f32_16x16x32_bf16 v[106:109], v[174:177], v[224:227], v[106:109]
	v_mfma_f32_16x16x32_bf16 v[94:97], v[166:169], v[232:235], v[94:97]
	v_mfma_f32_16x16x32_bf16 v[90:93], v[174:177], v[232:235], v[90:93]
	v_mfma_f32_16x16x32_bf16 v[78:81], v[166:169], v[240:243], v[78:81]
	v_mfma_f32_16x16x32_bf16 v[74:77], v[174:177], v[240:243], v[74:77]
	s_setprio 0
	s_setprio 1
	v_mfma_f32_16x16x32_bf16 v[118:121], v[182:185], v[212:215], v[118:121]
	v_mfma_f32_16x16x32_bf16 v[114:117], v[204:207], v[212:215], v[114:117]
	v_mfma_f32_16x16x32_bf16 v[102:105], v[182:185], v[220:223], v[102:105]
	v_mfma_f32_16x16x32_bf16 v[98:101], v[204:207], v[220:223], v[98:101]
	v_mfma_f32_16x16x32_bf16 v[86:89], v[182:185], v[228:231], v[86:89]
	v_mfma_f32_16x16x32_bf16 v[82:85], v[204:207], v[228:231], v[82:85]
	v_mfma_f32_16x16x32_bf16 v[70:73], v[182:185], v[236:239], v[70:73]
	v_mfma_f32_16x16x32_bf16 v[66:69], v[204:207], v[236:239], v[66:69]
	v_mfma_f32_16x16x32_bf16 v[118:121], v[186:189], v[216:219], v[118:121]
	v_mfma_f32_16x16x32_bf16 v[114:117], v[208:211], v[216:219], v[114:117]
	v_mfma_f32_16x16x32_bf16 v[102:105], v[186:189], v[224:227], v[102:105]
	v_mfma_f32_16x16x32_bf16 v[98:101], v[208:211], v[224:227], v[98:101]
	v_mfma_f32_16x16x32_bf16 v[86:89], v[186:189], v[232:235], v[86:89]
	v_mfma_f32_16x16x32_bf16 v[82:85], v[208:211], v[232:235], v[82:85]
	v_mfma_f32_16x16x32_bf16 v[70:73], v[186:189], v[240:243], v[70:73]
	v_mfma_f32_16x16x32_bf16 v[66:69], v[208:211], v[240:243], v[66:69]
	s_setprio 0
	s_barrier
	s_add_i32 s18, s47, s30
	v_lshl_add_u64 v[144:145], v[144:145], 0, s[80:81]
	s_mov_b32 m0, s18
	ds_read_b128 v[212:215], v164 offset:49152
	ds_read_b128 v[216:219], v164 offset:50176
	ds_read_b128 v[220:223], v164 offset:51200
	ds_read_b128 v[224:227], v164 offset:52224
	ds_read_b128 v[228:231], v164 offset:53248
	ds_read_b128 v[232:235], v164 offset:54272
	ds_read_b128 v[236:239], v164 offset:55296
	ds_read_b128 v[240:243], v164 offset:56320
	global_load_lds_dwordx4 v[144:145], off
	s_add_i32 m0, s18, 0x2000
	s_add_u32 s18, s22, 0x30080
	v_lshl_add_u64 v[144:145], v[178:179], 0, s[80:81]
	s_addc_u32 s19, s23, 0
	s_add_i32 s22, s48, s30
	global_load_lds_dwordx4 v[144:145], off
	v_lshl_add_u64 v[144:145], s[18:19], 0, v[0:1]
	s_mov_b32 m0, s22
	s_nop 0
	global_load_lds_dwordx4 v[144:145], off
	v_lshl_add_u64 v[144:145], s[18:19], 0, v[130:131]
	s_add_i32 m0, s22, 0x2000
	s_nop 0
	global_load_lds_dwordx4 v[144:145], off
	v_lshl_add_u64 v[144:145], v[190:191], 0, s[80:81]
	s_mov_b32 m0, s37
	s_nop 0
	global_load_lds_dwordx4 v[144:145], off
	v_lshl_add_u64 v[144:145], v[244:245], 0, s[80:81]
	s_mov_b32 m0, s38
	s_nop 0
	global_load_lds_dwordx4 v[144:145], off
	s_waitcnt vmcnt(8)
	s_waitcnt lgkmcnt(0)
	s_barrier
	s_setprio 1
	s_waitcnt lgkmcnt(0)
	v_mfma_f32_16x16x32_bf16 v[62:65], v[140:143], v[212:215], v[62:65]
	v_mfma_f32_16x16x32_bf16 v[58:61], v[170:173], v[212:215], v[58:61]
	v_mfma_f32_16x16x32_bf16 v[46:49], v[140:143], v[220:223], v[46:49]
	v_mfma_f32_16x16x32_bf16 v[42:45], v[170:173], v[220:223], v[42:45]
	v_mfma_f32_16x16x32_bf16 v[30:33], v[140:143], v[228:231], v[30:33]
	v_mfma_f32_16x16x32_bf16 v[26:29], v[170:173], v[228:231], v[26:29]
	v_mfma_f32_16x16x32_bf16 v[14:17], v[140:143], v[236:239], v[14:17]
	v_mfma_f32_16x16x32_bf16 v[10:13], v[170:173], v[236:239], v[10:13]
	v_mfma_f32_16x16x32_bf16 v[62:65], v[166:169], v[216:219], v[62:65]
	v_mfma_f32_16x16x32_bf16 v[58:61], v[174:177], v[216:219], v[58:61]
	v_mfma_f32_16x16x32_bf16 v[46:49], v[166:169], v[224:227], v[46:49]
	v_mfma_f32_16x16x32_bf16 v[42:45], v[174:177], v[224:227], v[42:45]
	v_mfma_f32_16x16x32_bf16 v[30:33], v[166:169], v[232:235], v[30:33]
	v_mfma_f32_16x16x32_bf16 v[26:29], v[174:177], v[232:235], v[26:29]
	v_mfma_f32_16x16x32_bf16 v[14:17], v[166:169], v[240:243], v[14:17]
	v_mfma_f32_16x16x32_bf16 v[10:13], v[174:177], v[240:243], v[10:13]
	s_setprio 0
	s_setprio 1
	v_mfma_f32_16x16x32_bf16 v[54:57], v[182:185], v[212:215], v[54:57]
	v_mfma_f32_16x16x32_bf16 v[50:53], v[204:207], v[212:215], v[50:53]
	v_mfma_f32_16x16x32_bf16 v[38:41], v[182:185], v[220:223], v[38:41]
	v_mfma_f32_16x16x32_bf16 v[34:37], v[204:207], v[220:223], v[34:37]
	v_mfma_f32_16x16x32_bf16 v[22:25], v[182:185], v[228:231], v[22:25]
	v_mfma_f32_16x16x32_bf16 v[18:21], v[204:207], v[228:231], v[18:21]
	v_mfma_f32_16x16x32_bf16 v[6:9], v[182:185], v[236:239], v[6:9]
	v_mfma_f32_16x16x32_bf16 v[2:5], v[204:207], v[236:239], v[2:5]
	v_mfma_f32_16x16x32_bf16 v[54:57], v[186:189], v[216:219], v[54:57]
	v_mfma_f32_16x16x32_bf16 v[50:53], v[208:211], v[216:219], v[50:53]
	v_mfma_f32_16x16x32_bf16 v[38:41], v[186:189], v[224:227], v[38:41]
	v_mfma_f32_16x16x32_bf16 v[34:37], v[208:211], v[224:227], v[34:37]
	v_mfma_f32_16x16x32_bf16 v[22:25], v[186:189], v[232:235], v[22:25]
	v_mfma_f32_16x16x32_bf16 v[18:21], v[208:211], v[232:235], v[18:21]
	v_mfma_f32_16x16x32_bf16 v[6:9], v[186:189], v[240:243], v[6:9]
	v_mfma_f32_16x16x32_bf16 v[2:5], v[208:211], v[240:243], v[2:5]
	s_add_i32 s46, s46, 2
	s_add_u32 s44, s44, 0x100
	s_addc_u32 s45, s45, 0
	s_cmp_gt_u32 s46, 9
	s_mov_b64 s[18:19], s[20:21]
	s_setprio 0
	s_barrier
	s_cbranch_scc0 .LBB0_1402
	s_and_b64 vcc, exec, s[14:15]
	s_cbranch_vccz .LBB0_1405
	s_barrier

.LBB0_1518:
	s_add_u32 s26, s24, 0x100
	s_addc_u32 s27, s25, 0
	s_add_i32 s54, 0, 0x10000
	s_cmp_eq_u32 s53, 12
	s_cselect_b32 s31, s19, s27
	s_cselect_b32 s30, s49, s26
	v_add_u32_e32 v140, s54, v143
	s_cselect_b32 s29, s17, s52
	s_cselect_b32 s28, s50, s51
	s_add_i32 s55, 0, 0x14000
	ds_read_b128 v[136:139], v140
	ds_read_b128 v[162:165], v140 offset:1024
	ds_read_b128 v[166:169], v140 offset:2048
	ds_read_b128 v[170:173], v140 offset:3072
	v_add_u32_e32 v140, s55, v143
	ds_read_b128 v[174:177], v140
	ds_read_b128 v[182:185], v140 offset:1024
	ds_read_b128 v[186:189], v140 offset:2048
	ds_read_b128 v[204:207], v140 offset:3072
	v_lshl_add_u64 v[140:141], s[24:25], 0, v[132:133]
	s_add_i32 m0, s39, 0xc000
	ds_read_b128 v[208:211], v145
	ds_read_b128 v[212:215], v145 offset:1024
	ds_read_b128 v[216:219], v145 offset:2048
	ds_read_b128 v[220:223], v145 offset:3072
	ds_read_b128 v[224:227], v145 offset:4096
	ds_read_b128 v[228:231], v145 offset:5120
	ds_read_b128 v[232:235], v145 offset:6144
	ds_read_b128 v[236:239], v145 offset:7168
	global_load_lds_dwordx4 v[140:141], off
	v_lshl_add_u64 v[140:141], s[24:25], 0, v[134:135]
	s_add_i32 m0, s39, 0xe000
	s_nop 0
	global_load_lds_dwordx4 v[140:141], off
	s_waitcnt vmcnt(8)
	s_waitcnt lgkmcnt(0)
	s_barrier
	s_setprio 1
	s_waitcnt lgkmcnt(0)
	v_mfma_f32_16x16x32_bf16 v[126:129], v[136:139], v[208:211], v[126:129]
	v_mfma_f32_16x16x32_bf16 v[122:125], v[166:169], v[208:211], v[122:125]
	v_mfma_f32_16x16x32_bf16 v[110:113], v[136:139], v[216:219], v[110:113]
	v_mfma_f32_16x16x32_bf16 v[106:109], v[166:169], v[216:219], v[106:109]
	v_mfma_f32_16x16x32_bf16 v[94:97], v[136:139], v[224:227], v[94:97]
	v_mfma_f32_16x16x32_bf16 v[90:93], v[166:169], v[224:227], v[90:93]
	v_mfma_f32_16x16x32_bf16 v[78:81], v[136:139], v[232:235], v[78:81]
	v_mfma_f32_16x16x32_bf16 v[74:77], v[166:169], v[232:235], v[74:77]
	v_mfma_f32_16x16x32_bf16 v[126:129], v[162:165], v[212:215], v[126:129]
	v_mfma_f32_16x16x32_bf16 v[122:125], v[170:173], v[212:215], v[122:125]
	v_mfma_f32_16x16x32_bf16 v[110:113], v[162:165], v[220:223], v[110:113]
	v_mfma_f32_16x16x32_bf16 v[106:109], v[170:173], v[220:223], v[106:109]
	v_mfma_f32_16x16x32_bf16 v[94:97], v[162:165], v[228:231], v[94:97]
	v_mfma_f32_16x16x32_bf16 v[90:93], v[170:173], v[228:231], v[90:93]
	v_mfma_f32_16x16x32_bf16 v[78:81], v[162:165], v[236:239], v[78:81]
	v_mfma_f32_16x16x32_bf16 v[74:77], v[170:173], v[236:239], v[74:77]
	s_setprio 0
	s_setprio 1
	v_mfma_f32_16x16x32_bf16 v[118:121], v[174:177], v[208:211], v[118:121]
	v_mfma_f32_16x16x32_bf16 v[114:117], v[186:189], v[208:211], v[114:117]
	v_mfma_f32_16x16x32_bf16 v[102:105], v[174:177], v[216:219], v[102:105]
	v_mfma_f32_16x16x32_bf16 v[98:101], v[186:189], v[216:219], v[98:101]
	v_mfma_f32_16x16x32_bf16 v[86:89], v[174:177], v[224:227], v[86:89]
	v_mfma_f32_16x16x32_bf16 v[82:85], v[186:189], v[224:227], v[82:85]
	v_mfma_f32_16x16x32_bf16 v[70:73], v[174:177], v[232:235], v[70:73]
	v_mfma_f32_16x16x32_bf16 v[66:69], v[186:189], v[232:235], v[66:69]
	v_mfma_f32_16x16x32_bf16 v[118:121], v[182:185], v[212:215], v[118:121]
	v_mfma_f32_16x16x32_bf16 v[114:117], v[204:207], v[212:215], v[114:117]
	v_mfma_f32_16x16x32_bf16 v[102:105], v[182:185], v[220:223], v[102:105]
	v_mfma_f32_16x16x32_bf16 v[98:101], v[204:207], v[220:223], v[98:101]
	v_mfma_f32_16x16x32_bf16 v[86:89], v[182:185], v[228:231], v[86:89]
	v_mfma_f32_16x16x32_bf16 v[82:85], v[204:207], v[228:231], v[82:85]
	v_mfma_f32_16x16x32_bf16 v[70:73], v[182:185], v[236:239], v[70:73]
	v_mfma_f32_16x16x32_bf16 v[66:69], v[204:207], v[236:239], v[66:69]
	s_setprio 0
	s_barrier
	s_add_i32 s24, s54, s38
	v_lshl_add_u64 v[140:141], s[28:29], 0, v[0:1]
	s_mov_b32 m0, s24
	ds_read_b128 v[208:211], v145 offset:16384
	ds_read_b128 v[212:215], v145 offset:17408
	ds_read_b128 v[216:219], v145 offset:18432
	ds_read_b128 v[220:223], v145 offset:19456
	ds_read_b128 v[224:227], v145 offset:20480
	ds_read_b128 v[228:231], v145 offset:21504
	ds_read_b128 v[232:235], v145 offset:22528
	ds_read_b128 v[236:239], v145 offset:23552
	global_load_lds_dwordx4 v[140:141], off
	s_add_i32 m0, s24, 0x2000
	s_add_u32 s24, s28, 0x40000
	v_lshl_add_u64 v[178:179], s[28:29], 0, v[130:131]
	s_addc_u32 s25, s29, 0
	s_add_i32 s54, s55, s38
	global_load_lds_dwordx4 v[178:179], off
	v_lshl_add_u64 v[190:191], s[24:25], 0, v[0:1]
	s_mov_b32 m0, s54
	v_lshl_add_u64 v[240:241], s[30:31], 0, v[130:131]
	global_load_lds_dwordx4 v[190:191], off
	v_lshl_add_u64 v[190:191], s[24:25], 0, v[130:131]
	s_add_i32 m0, s54, 0x2000
	s_nop 0
	global_load_lds_dwordx4 v[190:191], off
	v_lshl_add_u64 v[190:191], s[30:31], 0, v[0:1]
	s_mov_b32 m0, s39
	s_nop 0
	global_load_lds_dwordx4 v[190:191], off
	s_mov_b32 m0, s40
	s_nop 0
	global_load_lds_dwordx4 v[240:241], off
	s_waitcnt vmcnt(8)
	s_waitcnt lgkmcnt(0)
	s_barrier
	s_setprio 1
	s_waitcnt lgkmcnt(0)
	v_mfma_f32_16x16x32_bf16 v[62:65], v[136:139], v[208:211], v[62:65]
	v_mfma_f32_16x16x32_bf16 v[58:61], v[166:169], v[208:211], v[58:61]
	v_mfma_f32_16x16x32_bf16 v[46:49], v[136:139], v[216:219], v[46:49]
	v_mfma_f32_16x16x32_bf16 v[42:45], v[166:169], v[216:219], v[42:45]
	v_mfma_f32_16x16x32_bf16 v[30:33], v[136:139], v[224:227], v[30:33]
	v_mfma_f32_16x16x32_bf16 v[26:29], v[166:169], v[224:227], v[26:29]
	v_mfma_f32_16x16x32_bf16 v[14:17], v[136:139], v[232:235], v[14:17]
	v_mfma_f32_16x16x32_bf16 v[10:13], v[166:169], v[232:235], v[10:13]
	v_mfma_f32_16x16x32_bf16 v[62:65], v[162:165], v[212:215], v[62:65]
	v_mfma_f32_16x16x32_bf16 v[58:61], v[170:173], v[212:215], v[58:61]
	v_mfma_f32_16x16x32_bf16 v[46:49], v[162:165], v[220:223], v[46:49]
	v_mfma_f32_16x16x32_bf16 v[42:45], v[170:173], v[220:223], v[42:45]
	v_mfma_f32_16x16x32_bf16 v[30:33], v[162:165], v[228:231], v[30:33]
	v_mfma_f32_16x16x32_bf16 v[26:29], v[170:173], v[228:231], v[26:29]
	v_mfma_f32_16x16x32_bf16 v[14:17], v[162:165], v[236:239], v[14:17]
	v_mfma_f32_16x16x32_bf16 v[10:13], v[170:173], v[236:239], v[10:13]
	s_setprio 0
	s_setprio 1
	v_mfma_f32_16x16x32_bf16 v[54:57], v[174:177], v[208:211], v[54:57]
	v_mfma_f32_16x16x32_bf16 v[50:53], v[186:189], v[208:211], v[50:53]
	v_mfma_f32_16x16x32_bf16 v[38:41], v[174:177], v[216:219], v[38:41]
	v_mfma_f32_16x16x32_bf16 v[34:37], v[186:189], v[216:219], v[34:37]
	v_mfma_f32_16x16x32_bf16 v[22:25], v[174:177], v[224:227], v[22:25]
	v_mfma_f32_16x16x32_bf16 v[18:21], v[186:189], v[224:227], v[18:21]
	v_mfma_f32_16x16x32_bf16 v[6:9], v[174:177], v[232:235], v[6:9]
	v_mfma_f32_16x16x32_bf16 v[2:5], v[186:189], v[232:235], v[2:5]
	v_mfma_f32_16x16x32_bf16 v[54:57], v[182:185], v[212:215], v[54:57]
	v_mfma_f32_16x16x32_bf16 v[50:53], v[204:207], v[212:215], v[50:53]
	v_mfma_f32_16x16x32_bf16 v[38:41], v[182:185], v[220:223], v[38:41]
	v_mfma_f32_16x16x32_bf16 v[34:37], v[204:207], v[220:223], v[34:37]
	v_mfma_f32_16x16x32_bf16 v[22:25], v[182:185], v[228:231], v[22:25]
	v_mfma_f32_16x16x32_bf16 v[18:21], v[204:207], v[228:231], v[18:21]
	v_mfma_f32_16x16x32_bf16 v[6:9], v[182:185], v[236:239], v[6:9]
	v_mfma_f32_16x16x32_bf16 v[2:5], v[204:207], v[236:239], v[2:5]
	s_setprio 0
	s_barrier
	s_add_i32 s54, 0, 0x18000
	v_add_u32_e32 v160, s54, v143
	s_add_i32 s55, 0, 0x1c000
	ds_read_b128 v[136:139], v160
	ds_read_b128 v[162:165], v160 offset:1024
	ds_read_b128 v[166:169], v160 offset:2048
	ds_read_b128 v[170:173], v160 offset:3072
	v_add_u32_e32 v160, s55, v143
	ds_read_b128 v[174:177], v160
	ds_read_b128 v[182:185], v160 offset:1024
	ds_read_b128 v[186:189], v160 offset:2048
	ds_read_b128 v[204:207], v160 offset:3072
	s_add_u32 s24, s30, 0x40000
	s_addc_u32 s25, s31, 0
	s_mov_b32 m0, s41
	v_lshl_add_u64 v[242:243], s[24:25], 0, v[0:1]
	ds_read_b128 v[208:211], v145 offset:32768
	ds_read_b128 v[212:215], v145 offset:33792
	ds_read_b128 v[216:219], v145 offset:34816
	ds_read_b128 v[220:223], v145 offset:35840
	ds_read_b128 v[224:227], v145 offset:36864
	ds_read_b128 v[228:231], v145 offset:37888
	ds_read_b128 v[232:235], v145 offset:38912
	ds_read_b128 v[236:239], v145 offset:39936
	global_load_lds_dwordx4 v[242:243], off
	v_lshl_add_u64 v[242:243], s[24:25], 0, v[130:131]
	s_mov_b32 m0, s42
	s_nop 0
	global_load_lds_dwordx4 v[242:243], off
	s_waitcnt vmcnt(8)
	s_waitcnt lgkmcnt(0)
	s_barrier
	s_setprio 1
	s_waitcnt lgkmcnt(0)
	v_mfma_f32_16x16x32_bf16 v[126:129], v[136:139], v[208:211], v[126:129]
	v_mfma_f32_16x16x32_bf16 v[122:125], v[166:169], v[208:211], v[122:125]
	v_mfma_f32_16x16x32_bf16 v[110:113], v[136:139], v[216:219], v[110:113]
	v_mfma_f32_16x16x32_bf16 v[106:109], v[166:169], v[216:219], v[106:109]
	v_mfma_f32_16x16x32_bf16 v[94:97], v[136:139], v[224:227], v[94:97]
	v_mfma_f32_16x16x32_bf16 v[90:93], v[166:169], v[224:227], v[90:93]
	v_mfma_f32_16x16x32_bf16 v[78:81], v[136:139], v[232:235], v[78:81]
	v_mfma_f32_16x16x32_bf16 v[74:77], v[166:169], v[232:235], v[74:77]
	v_mfma_f32_16x16x32_bf16 v[126:129], v[162:165], v[212:215], v[126:129]
	v_mfma_f32_16x16x32_bf16 v[122:125], v[170:173], v[212:215], v[122:125]
	v_mfma_f32_16x16x32_bf16 v[110:113], v[162:165], v[220:223], v[110:113]
	v_mfma_f32_16x16x32_bf16 v[106:109], v[170:173], v[220:223], v[106:109]
	v_mfma_f32_16x16x32_bf16 v[94:97], v[162:165], v[228:231], v[94:97]
	v_mfma_f32_16x16x32_bf16 v[90:93], v[170:173], v[228:231], v[90:93]
	v_mfma_f32_16x16x32_bf16 v[78:81], v[162:165], v[236:239], v[78:81]
	v_mfma_f32_16x16x32_bf16 v[74:77], v[170:173], v[236:239], v[74:77]
	s_setprio 0
	s_setprio 1
	v_mfma_f32_16x16x32_bf16 v[118:121], v[174:177], v[208:211], v[118:121]
	v_mfma_f32_16x16x32_bf16 v[114:117], v[186:189], v[208:211], v[114:117]
	v_mfma_f32_16x16x32_bf16 v[102:105], v[174:177], v[216:219], v[102:105]
	v_mfma_f32_16x16x32_bf16 v[98:101], v[186:189], v[216:219], v[98:101]
	v_mfma_f32_16x16x32_bf16 v[86:89], v[174:177], v[224:227], v[86:89]
	v_mfma_f32_16x16x32_bf16 v[82:85], v[186:189], v[224:227], v[82:85]
	v_mfma_f32_16x16x32_bf16 v[70:73], v[174:177], v[232:235], v[70:73]
	v_mfma_f32_16x16x32_bf16 v[66:69], v[186:189], v[232:235], v[66:69]
	v_mfma_f32_16x16x32_bf16 v[118:121], v[182:185], v[212:215], v[118:121]
	v_mfma_f32_16x16x32_bf16 v[114:117], v[204:207], v[212:215], v[114:117]
	v_mfma_f32_16x16x32_bf16 v[102:105], v[182:185], v[220:223], v[102:105]
	v_mfma_f32_16x16x32_bf16 v[98:101], v[204:207], v[220:223], v[98:101]
	v_mfma_f32_16x16x32_bf16 v[86:89], v[182:185], v[228:231], v[86:89]
	v_mfma_f32_16x16x32_bf16 v[82:85], v[204:207], v[228:231], v[82:85]
	v_mfma_f32_16x16x32_bf16 v[70:73], v[182:185], v[236:239], v[70:73]
	v_mfma_f32_16x16x32_bf16 v[66:69], v[204:207], v[236:239], v[66:69]
	s_setprio 0
	s_barrier
	s_add_i32 s24, s54, s38
	v_lshl_add_u64 v[140:141], v[140:141], 0, s[80:81]
	s_mov_b32 m0, s24
	ds_read_b128 v[208:211], v145 offset:49152
	ds_read_b128 v[212:215], v145 offset:50176
	ds_read_b128 v[216:219], v145 offset:51200
	ds_read_b128 v[220:223], v145 offset:52224
	ds_read_b128 v[224:227], v145 offset:53248
	ds_read_b128 v[228:231], v145 offset:54272
	ds_read_b128 v[232:235], v145 offset:55296
	ds_read_b128 v[236:239], v145 offset:56320
	global_load_lds_dwordx4 v[140:141], off
	s_add_i32 m0, s24, 0x2000
	s_add_u32 s24, s28, 0x40080
	v_lshl_add_u64 v[140:141], v[178:179], 0, s[80:81]
	s_addc_u32 s25, s29, 0
	s_add_i32 s28, s55, s38
	global_load_lds_dwordx4 v[140:141], off
	v_lshl_add_u64 v[140:141], s[24:25], 0, v[0:1]
	s_mov_b32 m0, s28
	s_nop 0
	global_load_lds_dwordx4 v[140:141], off
	v_lshl_add_u64 v[140:141], s[24:25], 0, v[130:131]
	s_add_i32 m0, s28, 0x2000
	s_nop 0
	global_load_lds_dwordx4 v[140:141], off
	v_lshl_add_u64 v[140:141], v[190:191], 0, s[80:81]
	s_mov_b32 m0, s44
	s_nop 0
	global_load_lds_dwordx4 v[140:141], off
	v_lshl_add_u64 v[140:141], v[240:241], 0, s[80:81]
	s_mov_b32 m0, s45
	s_nop 0
	global_load_lds_dwordx4 v[140:141], off
	s_waitcnt vmcnt(8)
	s_waitcnt lgkmcnt(0)
	s_barrier
	s_setprio 1
	s_waitcnt lgkmcnt(0)
	v_mfma_f32_16x16x32_bf16 v[62:65], v[136:139], v[208:211], v[62:65]
	v_mfma_f32_16x16x32_bf16 v[58:61], v[166:169], v[208:211], v[58:61]
	v_mfma_f32_16x16x32_bf16 v[46:49], v[136:139], v[216:219], v[46:49]
	v_mfma_f32_16x16x32_bf16 v[42:45], v[166:169], v[216:219], v[42:45]
	v_mfma_f32_16x16x32_bf16 v[30:33], v[136:139], v[224:227], v[30:33]
	v_mfma_f32_16x16x32_bf16 v[26:29], v[166:169], v[224:227], v[26:29]
	v_mfma_f32_16x16x32_bf16 v[14:17], v[136:139], v[232:235], v[14:17]
	v_mfma_f32_16x16x32_bf16 v[10:13], v[166:169], v[232:235], v[10:13]
	v_mfma_f32_16x16x32_bf16 v[62:65], v[162:165], v[212:215], v[62:65]
	v_mfma_f32_16x16x32_bf16 v[58:61], v[170:173], v[212:215], v[58:61]
	v_mfma_f32_16x16x32_bf16 v[46:49], v[162:165], v[220:223], v[46:49]
	v_mfma_f32_16x16x32_bf16 v[42:45], v[170:173], v[220:223], v[42:45]
	v_mfma_f32_16x16x32_bf16 v[30:33], v[162:165], v[228:231], v[30:33]
	v_mfma_f32_16x16x32_bf16 v[26:29], v[170:173], v[228:231], v[26:29]
	v_mfma_f32_16x16x32_bf16 v[14:17], v[162:165], v[236:239], v[14:17]
	v_mfma_f32_16x16x32_bf16 v[10:13], v[170:173], v[236:239], v[10:13]
	s_setprio 0
	s_setprio 1
	v_mfma_f32_16x16x32_bf16 v[54:57], v[174:177], v[208:211], v[54:57]
	v_mfma_f32_16x16x32_bf16 v[50:53], v[186:189], v[208:211], v[50:53]
	v_mfma_f32_16x16x32_bf16 v[38:41], v[174:177], v[216:219], v[38:41]
	v_mfma_f32_16x16x32_bf16 v[34:37], v[186:189], v[216:219], v[34:37]
	v_mfma_f32_16x16x32_bf16 v[22:25], v[174:177], v[224:227], v[22:25]
	v_mfma_f32_16x16x32_bf16 v[18:21], v[186:189], v[224:227], v[18:21]
	v_mfma_f32_16x16x32_bf16 v[6:9], v[174:177], v[232:235], v[6:9]
	v_mfma_f32_16x16x32_bf16 v[2:5], v[186:189], v[232:235], v[2:5]
	v_mfma_f32_16x16x32_bf16 v[54:57], v[182:185], v[212:215], v[54:57]
	v_mfma_f32_16x16x32_bf16 v[50:53], v[204:207], v[212:215], v[50:53]
	v_mfma_f32_16x16x32_bf16 v[38:41], v[182:185], v[220:223], v[38:41]
	v_mfma_f32_16x16x32_bf16 v[34:37], v[204:207], v[220:223], v[34:37]
	v_mfma_f32_16x16x32_bf16 v[22:25], v[182:185], v[228:231], v[22:25]
	v_mfma_f32_16x16x32_bf16 v[18:21], v[204:207], v[228:231], v[18:21]
	v_mfma_f32_16x16x32_bf16 v[6:9], v[182:185], v[236:239], v[6:9]
	v_mfma_f32_16x16x32_bf16 v[2:5], v[204:207], v[236:239], v[2:5]
	s_add_i32 s53, s53, 2
	s_add_u32 s51, s51, 0x100
	s_addc_u32 s52, s52, 0
	s_cmp_gt_u32 s53, 13
	s_mov_b64 s[24:25], s[26:27]
	s_setprio 0
	s_barrier
	s_cbranch_scc0 .LBB0_1518
	s_and_b64 vcc, exec, s[14:15]
	s_cbranch_vccz .LBB0_1521
	s_barrier

.LBB0_1678:
	s_add_u32 s22, s20, 0x100
	s_addc_u32 s23, s21, 0
	s_add_i32 s50, 0, 0x10000
	s_cmp_eq_u32 s49, 40
	s_cselect_b32 s27, s9, s23
	s_cselect_b32 s26, s8, s22
	v_add_u32_e32 v140, s50, v143
	s_cselect_b32 s25, s19, s48
	s_cselect_b32 s24, s18, s47
	s_add_i32 s51, 0, 0x14000
	ds_read_b128 v[136:139], v140
	ds_read_b128 v[162:165], v140 offset:1024
	ds_read_b128 v[166:169], v140 offset:2048
	ds_read_b128 v[170:173], v140 offset:3072
	v_add_u32_e32 v140, s51, v143
	ds_read_b128 v[174:177], v140
	ds_read_b128 v[182:185], v140 offset:1024
	ds_read_b128 v[186:189], v140 offset:2048
	ds_read_b128 v[204:207], v140 offset:3072
	v_lshl_add_u64 v[140:141], s[20:21], 0, v[132:133]
	s_add_i32 m0, s35, 0xc000
	ds_read_b128 v[208:211], v145
	ds_read_b128 v[212:215], v145 offset:1024
	ds_read_b128 v[216:219], v145 offset:2048
	ds_read_b128 v[220:223], v145 offset:3072
	ds_read_b128 v[224:227], v145 offset:4096
	ds_read_b128 v[228:231], v145 offset:5120
	ds_read_b128 v[232:235], v145 offset:6144
	ds_read_b128 v[236:239], v145 offset:7168
	global_load_lds_dwordx4 v[140:141], off
	v_lshl_add_u64 v[140:141], s[20:21], 0, v[134:135]
	s_add_i32 m0, s35, 0xe000
	s_nop 0
	global_load_lds_dwordx4 v[140:141], off
	s_waitcnt vmcnt(8)
	s_waitcnt lgkmcnt(0)
	s_barrier
	s_setprio 1
	s_waitcnt lgkmcnt(0)
	v_mfma_f32_16x16x32_bf16 v[126:129], v[136:139], v[208:211], v[126:129]
	v_mfma_f32_16x16x32_bf16 v[122:125], v[166:169], v[208:211], v[122:125]
	v_mfma_f32_16x16x32_bf16 v[110:113], v[136:139], v[216:219], v[110:113]
	v_mfma_f32_16x16x32_bf16 v[106:109], v[166:169], v[216:219], v[106:109]
	v_mfma_f32_16x16x32_bf16 v[94:97], v[136:139], v[224:227], v[94:97]
	v_mfma_f32_16x16x32_bf16 v[90:93], v[166:169], v[224:227], v[90:93]
	v_mfma_f32_16x16x32_bf16 v[78:81], v[136:139], v[232:235], v[78:81]
	v_mfma_f32_16x16x32_bf16 v[74:77], v[166:169], v[232:235], v[74:77]
	v_mfma_f32_16x16x32_bf16 v[126:129], v[162:165], v[212:215], v[126:129]
	v_mfma_f32_16x16x32_bf16 v[122:125], v[170:173], v[212:215], v[122:125]
	v_mfma_f32_16x16x32_bf16 v[110:113], v[162:165], v[220:223], v[110:113]
	v_mfma_f32_16x16x32_bf16 v[106:109], v[170:173], v[220:223], v[106:109]
	v_mfma_f32_16x16x32_bf16 v[94:97], v[162:165], v[228:231], v[94:97]
	v_mfma_f32_16x16x32_bf16 v[90:93], v[170:173], v[228:231], v[90:93]
	v_mfma_f32_16x16x32_bf16 v[78:81], v[162:165], v[236:239], v[78:81]
	v_mfma_f32_16x16x32_bf16 v[74:77], v[170:173], v[236:239], v[74:77]
	s_setprio 0
	s_setprio 1
	v_mfma_f32_16x16x32_bf16 v[118:121], v[174:177], v[208:211], v[118:121]
	v_mfma_f32_16x16x32_bf16 v[114:117], v[186:189], v[208:211], v[114:117]
	v_mfma_f32_16x16x32_bf16 v[102:105], v[174:177], v[216:219], v[102:105]
	v_mfma_f32_16x16x32_bf16 v[98:101], v[186:189], v[216:219], v[98:101]
	v_mfma_f32_16x16x32_bf16 v[86:89], v[174:177], v[224:227], v[86:89]
	v_mfma_f32_16x16x32_bf16 v[82:85], v[186:189], v[224:227], v[82:85]
	v_mfma_f32_16x16x32_bf16 v[70:73], v[174:177], v[232:235], v[70:73]
	v_mfma_f32_16x16x32_bf16 v[66:69], v[186:189], v[232:235], v[66:69]
	v_mfma_f32_16x16x32_bf16 v[118:121], v[182:185], v[212:215], v[118:121]
	v_mfma_f32_16x16x32_bf16 v[114:117], v[204:207], v[212:215], v[114:117]
	v_mfma_f32_16x16x32_bf16 v[102:105], v[182:185], v[220:223], v[102:105]
	v_mfma_f32_16x16x32_bf16 v[98:101], v[204:207], v[220:223], v[98:101]
	v_mfma_f32_16x16x32_bf16 v[86:89], v[182:185], v[228:231], v[86:89]
	v_mfma_f32_16x16x32_bf16 v[82:85], v[204:207], v[228:231], v[82:85]
	v_mfma_f32_16x16x32_bf16 v[70:73], v[182:185], v[236:239], v[70:73]
	v_mfma_f32_16x16x32_bf16 v[66:69], v[204:207], v[236:239], v[66:69]
	s_setprio 0
	s_barrier
	s_add_i32 s20, s50, s34
	v_lshl_add_u64 v[140:141], s[24:25], 0, v[0:1]
	s_mov_b32 m0, s20
	ds_read_b128 v[208:211], v145 offset:16384
	ds_read_b128 v[212:215], v145 offset:17408
	ds_read_b128 v[216:219], v145 offset:18432
	ds_read_b128 v[220:223], v145 offset:19456
	ds_read_b128 v[224:227], v145 offset:20480
	ds_read_b128 v[228:231], v145 offset:21504
	ds_read_b128 v[232:235], v145 offset:22528
	ds_read_b128 v[236:239], v145 offset:23552
	global_load_lds_dwordx4 v[140:141], off
	s_add_i32 m0, s20, 0x2000
	s_add_u32 s20, s24, 0xb0000
	v_lshl_add_u64 v[178:179], s[24:25], 0, v[130:131]
	s_addc_u32 s21, s25, 0
	s_add_i32 s50, s51, s34
	global_load_lds_dwordx4 v[178:179], off
	v_lshl_add_u64 v[190:191], s[20:21], 0, v[0:1]
	s_mov_b32 m0, s50
	v_lshl_add_u64 v[240:241], s[26:27], 0, v[130:131]
	global_load_lds_dwordx4 v[190:191], off
	v_lshl_add_u64 v[190:191], s[20:21], 0, v[130:131]
	s_add_i32 m0, s50, 0x2000
	s_nop 0
	global_load_lds_dwordx4 v[190:191], off
	v_lshl_add_u64 v[190:191], s[26:27], 0, v[0:1]
	s_mov_b32 m0, s35
	s_nop 0
	global_load_lds_dwordx4 v[190:191], off
	s_mov_b32 m0, s36
	s_nop 0
	global_load_lds_dwordx4 v[240:241], off
	s_waitcnt vmcnt(8)
	s_waitcnt lgkmcnt(0)
	s_barrier
	s_setprio 1
	s_waitcnt lgkmcnt(0)
	v_mfma_f32_16x16x32_bf16 v[62:65], v[136:139], v[208:211], v[62:65]
	v_mfma_f32_16x16x32_bf16 v[58:61], v[166:169], v[208:211], v[58:61]
	v_mfma_f32_16x16x32_bf16 v[46:49], v[136:139], v[216:219], v[46:49]
	v_mfma_f32_16x16x32_bf16 v[42:45], v[166:169], v[216:219], v[42:45]
	v_mfma_f32_16x16x32_bf16 v[30:33], v[136:139], v[224:227], v[30:33]
	v_mfma_f32_16x16x32_bf16 v[26:29], v[166:169], v[224:227], v[26:29]
	v_mfma_f32_16x16x32_bf16 v[14:17], v[136:139], v[232:235], v[14:17]
	v_mfma_f32_16x16x32_bf16 v[10:13], v[166:169], v[232:235], v[10:13]
	v_mfma_f32_16x16x32_bf16 v[62:65], v[162:165], v[212:215], v[62:65]
	v_mfma_f32_16x16x32_bf16 v[58:61], v[170:173], v[212:215], v[58:61]
	v_mfma_f32_16x16x32_bf16 v[46:49], v[162:165], v[220:223], v[46:49]
	v_mfma_f32_16x16x32_bf16 v[42:45], v[170:173], v[220:223], v[42:45]
	v_mfma_f32_16x16x32_bf16 v[30:33], v[162:165], v[228:231], v[30:33]
	v_mfma_f32_16x16x32_bf16 v[26:29], v[170:173], v[228:231], v[26:29]
	v_mfma_f32_16x16x32_bf16 v[14:17], v[162:165], v[236:239], v[14:17]
	v_mfma_f32_16x16x32_bf16 v[10:13], v[170:173], v[236:239], v[10:13]
	s_setprio 0
	s_setprio 1
	v_mfma_f32_16x16x32_bf16 v[54:57], v[174:177], v[208:211], v[54:57]
	v_mfma_f32_16x16x32_bf16 v[50:53], v[186:189], v[208:211], v[50:53]
	v_mfma_f32_16x16x32_bf16 v[38:41], v[174:177], v[216:219], v[38:41]
	v_mfma_f32_16x16x32_bf16 v[34:37], v[186:189], v[216:219], v[34:37]
	v_mfma_f32_16x16x32_bf16 v[22:25], v[174:177], v[224:227], v[22:25]
	v_mfma_f32_16x16x32_bf16 v[18:21], v[186:189], v[224:227], v[18:21]
	v_mfma_f32_16x16x32_bf16 v[6:9], v[174:177], v[232:235], v[6:9]
	v_mfma_f32_16x16x32_bf16 v[2:5], v[186:189], v[232:235], v[2:5]
	v_mfma_f32_16x16x32_bf16 v[54:57], v[182:185], v[212:215], v[54:57]
	v_mfma_f32_16x16x32_bf16 v[50:53], v[204:207], v[212:215], v[50:53]
	v_mfma_f32_16x16x32_bf16 v[38:41], v[182:185], v[220:223], v[38:41]
	v_mfma_f32_16x16x32_bf16 v[34:37], v[204:207], v[220:223], v[34:37]
	v_mfma_f32_16x16x32_bf16 v[22:25], v[182:185], v[228:231], v[22:25]
	v_mfma_f32_16x16x32_bf16 v[18:21], v[204:207], v[228:231], v[18:21]
	v_mfma_f32_16x16x32_bf16 v[6:9], v[182:185], v[236:239], v[6:9]
	v_mfma_f32_16x16x32_bf16 v[2:5], v[204:207], v[236:239], v[2:5]
	s_setprio 0
	s_barrier
	s_add_i32 s50, 0, 0x18000
	v_add_u32_e32 v160, s50, v143
	s_add_i32 s51, 0, 0x1c000
	ds_read_b128 v[136:139], v160
	ds_read_b128 v[162:165], v160 offset:1024
	ds_read_b128 v[166:169], v160 offset:2048
	ds_read_b128 v[170:173], v160 offset:3072
	v_add_u32_e32 v160, s51, v143
	ds_read_b128 v[174:177], v160
	ds_read_b128 v[182:185], v160 offset:1024
	ds_read_b128 v[186:189], v160 offset:2048
	ds_read_b128 v[204:207], v160 offset:3072
	s_add_u32 s20, s26, 0xb0000
	s_addc_u32 s21, s27, 0
	s_mov_b32 m0, s37
	v_lshl_add_u64 v[242:243], s[20:21], 0, v[0:1]
	ds_read_b128 v[208:211], v145 offset:32768
	ds_read_b128 v[212:215], v145 offset:33792
	ds_read_b128 v[216:219], v145 offset:34816
	ds_read_b128 v[220:223], v145 offset:35840
	ds_read_b128 v[224:227], v145 offset:36864
	ds_read_b128 v[228:231], v145 offset:37888
	ds_read_b128 v[232:235], v145 offset:38912
	ds_read_b128 v[236:239], v145 offset:39936
	global_load_lds_dwordx4 v[242:243], off
	v_lshl_add_u64 v[242:243], s[20:21], 0, v[130:131]
	s_mov_b32 m0, s38
	s_nop 0
	global_load_lds_dwordx4 v[242:243], off
	s_waitcnt vmcnt(8)
	s_waitcnt lgkmcnt(0)
	s_barrier
	s_setprio 1
	s_waitcnt lgkmcnt(0)
	v_mfma_f32_16x16x32_bf16 v[126:129], v[136:139], v[208:211], v[126:129]
	v_mfma_f32_16x16x32_bf16 v[122:125], v[166:169], v[208:211], v[122:125]
	v_mfma_f32_16x16x32_bf16 v[110:113], v[136:139], v[216:219], v[110:113]
	v_mfma_f32_16x16x32_bf16 v[106:109], v[166:169], v[216:219], v[106:109]
	v_mfma_f32_16x16x32_bf16 v[94:97], v[136:139], v[224:227], v[94:97]
	v_mfma_f32_16x16x32_bf16 v[90:93], v[166:169], v[224:227], v[90:93]
	v_mfma_f32_16x16x32_bf16 v[78:81], v[136:139], v[232:235], v[78:81]
	v_mfma_f32_16x16x32_bf16 v[74:77], v[166:169], v[232:235], v[74:77]
	v_mfma_f32_16x16x32_bf16 v[126:129], v[162:165], v[212:215], v[126:129]
	v_mfma_f32_16x16x32_bf16 v[122:125], v[170:173], v[212:215], v[122:125]
	v_mfma_f32_16x16x32_bf16 v[110:113], v[162:165], v[220:223], v[110:113]
	v_mfma_f32_16x16x32_bf16 v[106:109], v[170:173], v[220:223], v[106:109]
	v_mfma_f32_16x16x32_bf16 v[94:97], v[162:165], v[228:231], v[94:97]
	v_mfma_f32_16x16x32_bf16 v[90:93], v[170:173], v[228:231], v[90:93]
	v_mfma_f32_16x16x32_bf16 v[78:81], v[162:165], v[236:239], v[78:81]
	v_mfma_f32_16x16x32_bf16 v[74:77], v[170:173], v[236:239], v[74:77]
	s_setprio 0
	s_setprio 1
	v_mfma_f32_16x16x32_bf16 v[118:121], v[174:177], v[208:211], v[118:121]
	v_mfma_f32_16x16x32_bf16 v[114:117], v[186:189], v[208:211], v[114:117]
	v_mfma_f32_16x16x32_bf16 v[102:105], v[174:177], v[216:219], v[102:105]
	v_mfma_f32_16x16x32_bf16 v[98:101], v[186:189], v[216:219], v[98:101]
	v_mfma_f32_16x16x32_bf16 v[86:89], v[174:177], v[224:227], v[86:89]
	v_mfma_f32_16x16x32_bf16 v[82:85], v[186:189], v[224:227], v[82:85]
	v_mfma_f32_16x16x32_bf16 v[70:73], v[174:177], v[232:235], v[70:73]
	v_mfma_f32_16x16x32_bf16 v[66:69], v[186:189], v[232:235], v[66:69]
	v_mfma_f32_16x16x32_bf16 v[118:121], v[182:185], v[212:215], v[118:121]
	v_mfma_f32_16x16x32_bf16 v[114:117], v[204:207], v[212:215], v[114:117]
	v_mfma_f32_16x16x32_bf16 v[102:105], v[182:185], v[220:223], v[102:105]
	v_mfma_f32_16x16x32_bf16 v[98:101], v[204:207], v[220:223], v[98:101]
	v_mfma_f32_16x16x32_bf16 v[86:89], v[182:185], v[228:231], v[86:89]
	v_mfma_f32_16x16x32_bf16 v[82:85], v[204:207], v[228:231], v[82:85]
	v_mfma_f32_16x16x32_bf16 v[70:73], v[182:185], v[236:239], v[70:73]
	v_mfma_f32_16x16x32_bf16 v[66:69], v[204:207], v[236:239], v[66:69]
	s_setprio 0
	s_barrier
	s_add_i32 s20, s50, s34
	v_lshl_add_u64 v[140:141], v[140:141], 0, s[80:81]
	s_mov_b32 m0, s20
	ds_read_b128 v[208:211], v145 offset:49152
	ds_read_b128 v[212:215], v145 offset:50176
	ds_read_b128 v[216:219], v145 offset:51200
	ds_read_b128 v[220:223], v145 offset:52224
	ds_read_b128 v[224:227], v145 offset:53248
	ds_read_b128 v[228:231], v145 offset:54272
	ds_read_b128 v[232:235], v145 offset:55296
	ds_read_b128 v[236:239], v145 offset:56320
	global_load_lds_dwordx4 v[140:141], off
	s_add_i32 m0, s20, 0x2000
	s_add_u32 s20, s24, 0xb0080
	v_lshl_add_u64 v[140:141], v[178:179], 0, s[80:81]
	s_addc_u32 s21, s25, 0
	s_add_i32 s24, s51, s34
	global_load_lds_dwordx4 v[140:141], off
	v_lshl_add_u64 v[140:141], s[20:21], 0, v[0:1]
	s_mov_b32 m0, s24
	s_nop 0
	global_load_lds_dwordx4 v[140:141], off
	v_lshl_add_u64 v[140:141], s[20:21], 0, v[130:131]
	s_add_i32 m0, s24, 0x2000
	s_nop 0
	global_load_lds_dwordx4 v[140:141], off
	v_lshl_add_u64 v[140:141], v[190:191], 0, s[80:81]
	s_mov_b32 m0, s40
	s_nop 0
	global_load_lds_dwordx4 v[140:141], off
	v_lshl_add_u64 v[140:141], v[240:241], 0, s[80:81]
	s_mov_b32 m0, s41
	s_nop 0
	global_load_lds_dwordx4 v[140:141], off
	s_waitcnt vmcnt(8)
	s_waitcnt lgkmcnt(0)
	s_barrier
	s_setprio 1
	s_waitcnt lgkmcnt(0)
	v_mfma_f32_16x16x32_bf16 v[62:65], v[136:139], v[208:211], v[62:65]
	v_mfma_f32_16x16x32_bf16 v[58:61], v[166:169], v[208:211], v[58:61]
	v_mfma_f32_16x16x32_bf16 v[46:49], v[136:139], v[216:219], v[46:49]
	v_mfma_f32_16x16x32_bf16 v[42:45], v[166:169], v[216:219], v[42:45]
	v_mfma_f32_16x16x32_bf16 v[30:33], v[136:139], v[224:227], v[30:33]
	v_mfma_f32_16x16x32_bf16 v[26:29], v[166:169], v[224:227], v[26:29]
	v_mfma_f32_16x16x32_bf16 v[14:17], v[136:139], v[232:235], v[14:17]
	v_mfma_f32_16x16x32_bf16 v[10:13], v[166:169], v[232:235], v[10:13]
	v_mfma_f32_16x16x32_bf16 v[62:65], v[162:165], v[212:215], v[62:65]
	v_mfma_f32_16x16x32_bf16 v[58:61], v[170:173], v[212:215], v[58:61]
	v_mfma_f32_16x16x32_bf16 v[46:49], v[162:165], v[220:223], v[46:49]
	v_mfma_f32_16x16x32_bf16 v[42:45], v[170:173], v[220:223], v[42:45]
	v_mfma_f32_16x16x32_bf16 v[30:33], v[162:165], v[228:231], v[30:33]
	v_mfma_f32_16x16x32_bf16 v[26:29], v[170:173], v[228:231], v[26:29]
	v_mfma_f32_16x16x32_bf16 v[14:17], v[162:165], v[236:239], v[14:17]
	v_mfma_f32_16x16x32_bf16 v[10:13], v[170:173], v[236:239], v[10:13]
	s_setprio 0
	s_setprio 1
	v_mfma_f32_16x16x32_bf16 v[54:57], v[174:177], v[208:211], v[54:57]
	v_mfma_f32_16x16x32_bf16 v[50:53], v[186:189], v[208:211], v[50:53]
	v_mfma_f32_16x16x32_bf16 v[38:41], v[174:177], v[216:219], v[38:41]
	v_mfma_f32_16x16x32_bf16 v[34:37], v[186:189], v[216:219], v[34:37]
	v_mfma_f32_16x16x32_bf16 v[22:25], v[174:177], v[224:227], v[22:25]
	v_mfma_f32_16x16x32_bf16 v[18:21], v[186:189], v[224:227], v[18:21]
	v_mfma_f32_16x16x32_bf16 v[6:9], v[174:177], v[232:235], v[6:9]
	v_mfma_f32_16x16x32_bf16 v[2:5], v[186:189], v[232:235], v[2:5]
	v_mfma_f32_16x16x32_bf16 v[54:57], v[182:185], v[212:215], v[54:57]
	v_mfma_f32_16x16x32_bf16 v[50:53], v[204:207], v[212:215], v[50:53]
	v_mfma_f32_16x16x32_bf16 v[38:41], v[182:185], v[220:223], v[38:41]
	v_mfma_f32_16x16x32_bf16 v[34:37], v[204:207], v[220:223], v[34:37]
	v_mfma_f32_16x16x32_bf16 v[22:25], v[182:185], v[228:231], v[22:25]
	v_mfma_f32_16x16x32_bf16 v[18:21], v[204:207], v[228:231], v[18:21]
	v_mfma_f32_16x16x32_bf16 v[6:9], v[182:185], v[236:239], v[6:9]
	v_mfma_f32_16x16x32_bf16 v[2:5], v[204:207], v[236:239], v[2:5]
	s_add_i32 s49, s49, 2
	s_add_u32 s47, s47, 0x100
	s_addc_u32 s48, s48, 0
	s_cmp_gt_u32 s49, 41
	s_mov_b64 s[20:21], s[22:23]
	s_setprio 0
	s_barrier
	s_cbranch_scc0 .LBB0_1678
	s_and_b64 vcc, exec, s[16:17]
	s_cbranch_vccz .LBB0_1681
	s_barrier
